# v5: v4 + merge0/merge1 round-2 tiles as half tiles on all workgroups, FFN weight conversion spread over all workgroups
# baseline (speedup 1.0000x reference)
.LBB0_837:
	s_or_b64 exec, exec, s[6:7]
	s_and_b64 vcc, exec, s[4:5]
	s_waitcnt lgkmcnt(0)
	s_barrier
	s_nop 0
	s_mov_b32 s4, s2
	s_add_i32 s28, s4, 0x600
	s_cmpk_gt_i32 s28, 0x9ff
	s_cbranch_scc1 .LBB0_863
	s_load_dwordx2 s[4:5], s[0:1], 0x108
	s_load_dwordx2 s[6:7], s[0:1], 0xe8
	s_load_dwordx2 s[8:9], s[0:1], 0xd8
	s_load_dwordx2 s[10:11], s[0:1], 0x50
	s_mov_b32 s36, 0x1400000
	s_waitcnt lgkmcnt(0)
	s_add_u32 s12, s4, 0x2000000
	s_addc_u32 s13, s5, 0
	s_add_u32 s14, s4, 0x1800000
	s_addc_u32 s15, s5, 0
	s_lshl_b32 s16, s56, 1
	s_mov_b32 s17, 0
	s_sub_i32 s30, s16, s17
	s_lshl_b32 s16, s56, 3
	s_mov_b32 s17, 0
	s_sub_i32 s33, s16, s17
	s_lshl_b32 s16, s56, 6
	s_mov_b32 s17, 0
	s_lshl_b32 s29, s28, 1
	s_lshl_b32 s31, s28, 3
	s_lshl_b32 s34, s28, 6
	s_sub_i32 s35, s16, s17
	s_mov_b32 s17, 0
	v_mov_b32_e32 v1, 0
	s_movk_i32 s37, 0x204
	s_branch .LBB0_843

.LBB0_842:
	s_waitcnt vmcnt(3)
	v_mov_b32_e32 v18, v234
	s_ashr_i32 s27, s26, 31
	s_lshl_b64 s[26:27], s[26:27], 2
	v_ashrrev_i32_e32 v19, 5, v18
	s_waitcnt lgkmcnt(0)
	s_add_u32 s24, s24, s26
	v_lshlrev_b32_e32 v0, 4, v18
	v_add_u32_e32 v2, s16, v19
	s_addc_u32 s25, s25, s27
	v_and_b32_e32 v0, 0x1f0, v0
	v_ashrrev_i32_e32 v3, 31, v2
	v_lshl_add_u64 v[14:15], s[24:25], 0, v[0:1]
	v_mul_lo_u32 v4, s22, v3
	v_mul_lo_u32 v5, s23, v2
	v_mad_u64_u32 v[2:3], s[24:25], s22, v2, 0
	v_add3_u32 v3, v3, v4, v5
	v_lshl_add_u64 v[10:11], v[2:3], 2, v[14:15]
	v_add_u32_e32 v2, 0x200, v18
	s_waitcnt vmcnt(2)
	v_ashrrev_i32_e32 v22, 5, v2
	v_add_u32_e32 v2, s16, v22
	v_ashrrev_i32_e32 v3, 31, v2
	v_mul_lo_u32 v4, s22, v3
	v_mul_lo_u32 v5, s23, v2
	v_mad_u64_u32 v[2:3], s[24:25], s22, v2, 0
	v_add3_u32 v3, v3, v4, v5
	v_lshl_add_u64 v[12:13], v[2:3], 2, v[14:15]
	global_load_dwordx4 v[2:5], v[10:11], off
	global_load_dwordx4 v[6:9], v[12:13], off
	v_add_u32_e32 v10, 0x400, v18
	v_ashrrev_i32_e32 v24, 5, v10
	v_add_u32_e32 v10, s16, v24
	v_add_u32_e32 v16, 0x600, v18
	v_ashrrev_i32_e32 v11, 31, v10
	s_waitcnt vmcnt(3)
	v_ashrrev_i32_e32 v26, 5, v16
	v_mul_lo_u32 v12, s22, v11
	v_mul_lo_u32 v13, s23, v10
	v_mad_u64_u32 v[10:11], s[24:25], s22, v10, 0
	v_add_u32_e32 v16, s16, v26
	v_add3_u32 v11, v11, v12, v13
	v_ashrrev_i32_e32 v17, 31, v16
	v_lshl_add_u64 v[10:11], v[10:11], 2, v[14:15]
	v_mul_lo_u32 v20, s22, v17
	v_mul_lo_u32 v21, s23, v16
	v_mad_u64_u32 v[16:17], s[22:23], s22, v16, 0
	global_load_dwordx4 v[10:13], v[10:11], off
	v_add3_u32 v17, v17, v20, v21
	v_lshl_add_u64 v[14:15], v[16:17], 2, v[14:15]
	global_load_dwordx4 v[14:17], v[14:15], off
	v_ashrrev_i32_e32 v27, 3, v18
	v_lshlrev_b32_e32 v18, 3, v18
	v_and_b32_e32 v20, 56, v18
	v_add_u32_e32 v18, 0, v0
	v_lshlrev_b32_e32 v28, 2, v27
	v_mul_u32_u24_e32 v29, 0x204, v20
	v_lshlrev_b32_e32 v0, 1, v20
	v_mad_u64_u32 v[20:21], s[24:25], v19, s37, v[18:19]
	v_add3_u32 v21, 0, v29, v28
	v_mad_u64_u32 v[22:23], s[24:25], v22, s37, v[18:19]
	v_mad_u64_u32 v[24:25], s[24:25], v24, s37, v[18:19]
	v_mad_u64_u32 v[18:19], s[24:25], v26, s37, v[18:19]
	s_lshl_b64 s[22:23], s[16:17], 1
	v_add_u32_e32 v19, 8, v21
	v_add_u32_e32 v23, 12, v21
	v_add_u32_e32 v25, 16, v21
	s_add_u32 s20, s20, s22
	s_addc_u32 s21, s21, s23
	s_mov_b32 s16, s28
	s_add_i32 s28, s16, s56
	s_add_i32 s29, s29, s30
	s_add_i32 s31, s31, s33
	s_add_i32 s34, s34, s35
	s_cmpk_lt_i32 s28, 0xa00
	s_waitcnt vmcnt(3)
	ds_write2_b32 v20, v2, v3 offset1:1
	ds_write2_b32 v20, v4, v5 offset0:2 offset1:3
	s_waitcnt vmcnt(2)
	ds_write2_b32 v22, v6, v7 offset1:1
	ds_write2_b32 v22, v8, v9 offset0:2 offset1:3
	s_waitcnt vmcnt(1)
	ds_write2_b32 v24, v10, v11 offset1:1
	ds_write2_b32 v24, v12, v13 offset0:2 offset1:3
	s_waitcnt vmcnt(0)
	ds_write2_b32 v18, v14, v15 offset1:1
	ds_write2_b32 v18, v16, v17 offset0:2 offset1:3
	v_add_u32_e32 v2, 20, v21
	s_waitcnt lgkmcnt(0)
	s_barrier
	ds_read2st64_b32 v[6:7], v21 offset1:1
	ds_read2_b32 v[8:9], v21 offset0:129 offset1:193
	ds_read2st64_b32 v[10:11], v19 offset0:4 offset1:5
	ds_read2st64_b32 v[12:13], v23 offset0:6 offset1:7
	ds_read2st64_b32 v[14:15], v25 offset0:8 offset1:9
	ds_read2st64_b32 v[16:17], v2 offset0:10 offset1:11
	v_add_u32_e32 v2, 24, v21
	ds_read2st64_b32 v[18:19], v2 offset0:12 offset1:13
	v_add_u32_e32 v2, 28, v21
	ds_read2st64_b32 v[20:21], v2 offset0:14 offset1:15
	v_lshl_add_u64 v[22:23], s[20:21], 0, v[0:1]
	v_add_u32_e32 v0, s38, v27
	s_waitcnt lgkmcnt(6)
	v_cvt_pk_bf16_f32 v2, v6, v8
	v_ashrrev_i32_e32 v6, 31, v0
	v_mul_lo_u32 v6, s18, v6
	v_mul_lo_u32 v8, s19, v0
	v_mad_u64_u32 v[24:25], s[20:21], s18, v0, 0
	v_add3_u32 v25, v25, v6, v8
	v_add_u32_e32 v0, 64, v0
	s_waitcnt lgkmcnt(4)
	v_cvt_pk_bf16_f32 v3, v10, v12
	s_waitcnt lgkmcnt(2)
	v_cvt_pk_bf16_f32 v4, v14, v16
	s_waitcnt lgkmcnt(0)
	v_cvt_pk_bf16_f32 v5, v18, v20
	v_lshl_add_u64 v[24:25], v[24:25], 1, v[22:23]
	v_ashrrev_i32_e32 v6, 31, v0
	global_store_dwordx4 v[24:25], v[2:5], off
	v_mul_lo_u32 v8, s18, v6
	s_nop 0
	v_cvt_pk_bf16_f32 v2, v7, v9
	v_mul_lo_u32 v9, s19, v0
	v_mad_u64_u32 v[6:7], s[18:19], s18, v0, 0
	v_add3_u32 v7, v7, v8, v9
	v_cvt_pk_bf16_f32 v3, v11, v13
	v_cvt_pk_bf16_f32 v4, v15, v17
	v_cvt_pk_bf16_f32 v5, v19, v21
	v_lshl_add_u64 v[6:7], v[6:7], 1, v[22:23]
	global_store_dwordx4 v[6:7], v[2:5], off
	s_barrier
	s_cbranch_scc0 .LBB0_863

.LBB0_869:
	s_add_i32 s40, s40, 1
	s_mul_i32 s4, s40, s45
	s_mul_hi_u32 s5, s40, s46
	s_add_i32 s5, s5, s4
	s_mul_i32 s4, s40, s46
	s_add_u32 s26, s4, s2
	s_addc_u32 s27, s5, s47
	s_cmp_eq_u32 s40, 1
	s_cbranch_scc0 .Lm0_enum_skip
	s_cmp_eq_u32 s46, 0x100
	s_cbranch_scc0 .Lm0_enum_skip
	s_lshr_b32 s26, s2, 1
	s_add_u32 s26, s26, 0x100
	s_mov_b32 s27, 0
.Lm0_enum_skip:
	v_cmp_gt_i64_e32 vcc, s[26:27], v[144:145]
	v_cmp_lt_i64_e64 s[4:5], s[26:27], v[142:143]
	s_cbranch_vccnz .LBB0_871
	s_mul_hi_i32 s20, s26, 0x2aaaaaab
	s_lshr_b32 s21, s20, 31
	s_ashr_i32 s20, s20, 6
	s_add_i32 s20, s20, s21
	s_mul_i32 s21, s20, 0xfffffe80
	s_add_i32 s21, s21, s26
	s_ashr_i32 s22, s21, 31
	s_lshr_b32 s22, s22, 29
	s_add_i32 s22, s21, s22
	s_ashr_i32 s23, s22, 3
	s_and_b32 s22, s22, -8
	s_sub_i32 s21, s21, s22
	s_cmp_lt_i32 s21, 0
	s_cselect_b32 s22, 49, 48
	s_mul_i32 s21, s22, s21
	s_add_i32 s21, s21, s23
	s_ashr_i32 s22, s21, 31
	s_lshr_b32 s22, s22, 27
	s_add_i32 s22, s21, s22
	s_ashr_i32 s23, s22, 5
	s_lshl_b32 s23, s23, 3
	s_sub_i32 s24, 0x60, s23
	s_min_i32 s24, s24, 8
	s_abs_i32 s25, s24
	v_cvt_f32_u32_e32 v2, s25
	s_sub_i32 s27, 0, s25
	s_andn2_b32 s22, s22, 31
	s_sub_i32 s21, s21, s22
	v_rcp_iflag_f32_e32 v2, v2
	s_abs_i32 s22, s21
	s_xor_b32 s26, s21, s24
	s_ashr_i32 s26, s26, 31
	v_mul_f32_e32 v2, 0x4f7ffffe, v2
	v_cvt_u32_f32_e32 v2, v2
	s_nop 0
	v_readfirstlane_b32 s36, v2
	s_mul_i32 s27, s27, s36
	s_mul_hi_u32 s27, s36, s27
	s_add_i32 s36, s36, s27
	s_mul_hi_u32 s27, s22, s36
	s_mul_i32 s36, s27, s25
	s_sub_i32 s22, s22, s36
	s_add_i32 s37, s27, 1
	s_sub_i32 s36, s22, s25
	s_cmp_ge_u32 s22, s25
	s_cselect_b32 s27, s37, s27
	s_cselect_b32 s22, s36, s22
	s_add_i32 s36, s27, 1
	s_cmp_ge_u32 s22, s25
	s_cselect_b32 s22, s36, s27
	s_xor_b32 s22, s22, s26
	s_sub_i32 s22, s22, s26
	s_mul_i32 s24, s22, s24
	s_sub_i32 s21, s21, s24
	s_add_i32 s24, s21, s23
.LBB0_871:
	s_ashr_i32 s25, s24, 31
	s_lshl_b64 s[26:27], s[24:25], 19
	s_cmp_eq_u32 s40, 1
	s_cbranch_scc0 .Lm0_a_skip
	s_cmp_eq_u32 s46, 0x100
	s_cbranch_scc0 .Lm0_a_skip
	s_and_b32 s98, s2, 1
	s_lshl_b32 s98, s98, 18
	s_or_b32 s26, s26, s98
.Lm0_a_skip:
	s_add_u32 s23, s62, s26
	s_addc_u32 s25, s63, s27
	s_ashr_i32 s21, s20, 31
	s_lshl_b64 s[36:37], s[20:21], 11
	s_add_u32 s26, s23, s36
	s_addc_u32 s27, s25, s37
	s_and_b64 s[50:51], s[4:5], exec
	s_cselect_b32 s21, s27, s35
	s_cselect_b32 s25, s26, s34
	s_ashr_i32 s23, s22, 31
	s_lshl_b64 s[50:51], s[22:23], 19
	v_lshl_add_u64 v[2:3], v[128:129], 0, s[50:51]
	v_lshl_add_u64 v[146:147], v[2:3], 0, s[36:37]
	v_cndmask_b32_e64 v148, v0, v146, s[4:5]
	s_add_u32 s34, s34, 0x40080
	v_lshl_add_u64 v[150:151], v[0:1], 0, s[18:19]
	v_mov_b32_e32 v0, 0
	v_cndmask_b32_e64 v149, v1, v147, s[4:5]
	s_addc_u32 s35, s35, 0
	s_mov_b32 s23, -2
	v_mov_b32_e32 v1, v0
	v_mov_b32_e32 v2, v0
	v_mov_b32_e32 v3, v0
	v_mov_b32_e32 v4, v0
	v_mov_b32_e32 v5, v0
	v_mov_b32_e32 v6, v0
	v_mov_b32_e32 v7, v0
	v_mov_b32_e32 v8, v0
	v_mov_b32_e32 v9, v0
	v_mov_b32_e32 v10, v0
	v_mov_b32_e32 v11, v0
	v_mov_b32_e32 v12, v0
	v_mov_b32_e32 v13, v0
	v_mov_b32_e32 v14, v0
	v_mov_b32_e32 v15, v0
	s_waitcnt vmcnt(0)
	v_mov_b32_e32 v32, v0
	v_mov_b32_e32 v33, v0
	v_mov_b32_e32 v34, v0
	v_mov_b32_e32 v35, v0
	v_mov_b32_e32 v36, v0
	v_mov_b32_e32 v37, v0
	v_mov_b32_e32 v38, v0
	v_mov_b32_e32 v39, v0
	v_mov_b32_e32 v40, v0
	v_mov_b32_e32 v41, v0
	v_mov_b32_e32 v42, v0
	v_mov_b32_e32 v43, v0
	v_mov_b32_e32 v44, v0
	v_mov_b32_e32 v45, v0
	v_mov_b32_e32 v46, v0
	v_mov_b32_e32 v47, v0
	v_mov_b32_e32 v16, v0
	v_mov_b32_e32 v17, v0
	v_mov_b32_e32 v18, v0
	v_mov_b32_e32 v19, v0
	v_mov_b32_e32 v20, v0
	v_mov_b32_e32 v21, v0
	v_mov_b32_e32 v22, v0
	v_mov_b32_e32 v23, v0
	v_mov_b32_e32 v24, v0
	v_mov_b32_e32 v25, v0
	v_mov_b32_e32 v26, v0
	v_mov_b32_e32 v27, v0
	v_mov_b32_e32 v28, v0
	v_mov_b32_e32 v29, v0
	v_mov_b32_e32 v30, v0
	v_mov_b32_e32 v31, v0
	v_mov_b32_e32 v48, v0
	v_mov_b32_e32 v49, v0
	v_mov_b32_e32 v50, v0
	v_mov_b32_e32 v51, v0
	v_mov_b32_e32 v52, v0
	v_mov_b32_e32 v53, v0
	v_mov_b32_e32 v54, v0
	v_mov_b32_e32 v55, v0
	v_mov_b32_e32 v56, v0
	v_mov_b32_e32 v57, v0
	v_mov_b32_e32 v58, v0
	v_mov_b32_e32 v59, v0
	v_mov_b32_e32 v60, v0
	v_mov_b32_e32 v61, v0
	v_mov_b32_e32 v62, v0
	v_mov_b32_e32 v63, v0
	v_mov_b32_e32 v64, v0
	v_mov_b32_e32 v65, v0
	v_mov_b32_e32 v66, v0
	v_mov_b32_e32 v67, v0
	v_mov_b32_e32 v68, v0
	v_mov_b32_e32 v69, v0
	v_mov_b32_e32 v70, v0
	v_mov_b32_e32 v71, v0
	v_mov_b32_e32 v72, v0
	v_mov_b32_e32 v73, v0
	v_mov_b32_e32 v74, v0
	v_mov_b32_e32 v75, v0
	v_mov_b32_e32 v76, v0
	v_mov_b32_e32 v77, v0
	v_mov_b32_e32 v78, v0
	v_mov_b32_e32 v79, v0
	v_mov_b32_e32 v96, v0
	v_mov_b32_e32 v97, v0
	v_mov_b32_e32 v98, v0
	v_mov_b32_e32 v99, v0
	v_mov_b32_e32 v100, v0
	v_mov_b32_e32 v101, v0
	v_mov_b32_e32 v102, v0
	v_mov_b32_e32 v103, v0
	v_mov_b32_e32 v108, v0
	v_mov_b32_e32 v109, v0
	v_mov_b32_e32 v110, v0
	v_mov_b32_e32 v111, v0
	v_mov_b32_e32 v116, v0
	v_mov_b32_e32 v117, v0
	v_mov_b32_e32 v118, v0
	v_mov_b32_e32 v119, v0
	v_mov_b32_e32 v80, v0
	v_mov_b32_e32 v81, v0
	v_mov_b32_e32 v82, v0
	v_mov_b32_e32 v83, v0
	v_mov_b32_e32 v84, v0
	v_mov_b32_e32 v85, v0
	v_mov_b32_e32 v86, v0
	v_mov_b32_e32 v87, v0
	v_mov_b32_e32 v88, v0
	v_mov_b32_e32 v89, v0
	v_mov_b32_e32 v90, v0
	v_mov_b32_e32 v91, v0
	v_mov_b32_e32 v92, v0
	v_mov_b32_e32 v93, v0
	v_mov_b32_e32 v94, v0
	v_mov_b32_e32 v95, v0
	v_mov_b32_e32 v104, v0
	v_mov_b32_e32 v105, v0
	v_mov_b32_e32 v106, v0
	v_mov_b32_e32 v107, v0
	v_mov_b32_e32 v112, v0
	v_mov_b32_e32 v113, v0
	v_mov_b32_e32 v114, v0
	v_mov_b32_e32 v115, v0
	v_mov_b32_e32 v120, v0
	v_mov_b32_e32 v121, v0
	v_mov_b32_e32 v122, v0
	v_mov_b32_e32 v123, v0
	v_mov_b32_e32 v124, v0
	v_mov_b32_e32 v125, v0
	v_mov_b32_e32 v126, v0
	v_mov_b32_e32 v127, v0
.LBB0_872:
	ds_read_b128 v[164:167], v155
	ds_read_b128 v[168:171], v155 offset:1024
	ds_read_b128 v[172:175], v155 offset:2048
	ds_read_b128 v[176:179], v155 offset:3072
	ds_read_b128 v[180:183], v156
	ds_read_b128 v[188:191], v156 offset:1024
	ds_read_b128 v[192:195], v156 offset:2048
	ds_read_b128 v[196:199], v156 offset:3072
	s_add_u32 s50, s34, 0xfffc0080
	s_addc_u32 s51, s35, -1
	s_cmp_eq_u32 s23, 12
	s_cselect_b64 vcc, -1, 0
	s_and_b64 s[36:37], vcc, exec
	v_cndmask_b32_e32 v159, v151, v149, vcc
	s_cselect_b32 s37, s21, s51
	s_cselect_b32 s36, s25, s50
	v_cndmask_b32_e32 v158, v150, v148, vcc
	v_lshl_add_u64 v[232:233], s[34:35], 0, v[138:139]
	s_add_i32 m0, s29, 0xc000
	ds_read_b128 v[200:203], v157
	ds_read_b128 v[204:207], v157 offset:1024
	ds_read_b128 v[208:211], v157 offset:2048
	ds_read_b128 v[212:215], v157 offset:3072
	ds_read_b128 v[216:219], v157 offset:4096
	ds_read_b128 v[220:223], v157 offset:5120
	ds_read_b128 v[224:227], v157 offset:6144
	ds_read_b128 v[228:231], v157 offset:7168
	global_load_lds_dwordx4 v[232:233], off
	v_lshl_add_u64 v[232:233], s[34:35], 0, v[140:141]
	s_add_i32 m0, s29, 0xe000
	s_nop 0
	global_load_lds_dwordx4 v[232:233], off
	s_waitcnt vmcnt(8)
	s_waitcnt lgkmcnt(0)
	s_barrier
	s_setprio 1
	s_waitcnt lgkmcnt(0)
	v_mfma_f32_16x16x32_bf16 v[124:127], v[164:167], v[200:203], v[124:127]
	v_mfma_f32_16x16x32_bf16 v[120:123], v[172:175], v[200:203], v[120:123]
	v_mfma_f32_16x16x32_bf16 v[112:115], v[164:167], v[208:211], v[112:115]
	v_mfma_f32_16x16x32_bf16 v[104:107], v[172:175], v[208:211], v[104:107]
	v_mfma_f32_16x16x32_bf16 v[92:95], v[164:167], v[216:219], v[92:95]
	v_mfma_f32_16x16x32_bf16 v[88:91], v[172:175], v[216:219], v[88:91]
	v_mfma_f32_16x16x32_bf16 v[84:87], v[164:167], v[224:227], v[84:87]
	v_mfma_f32_16x16x32_bf16 v[80:83], v[172:175], v[224:227], v[80:83]
	v_mfma_f32_16x16x32_bf16 v[124:127], v[168:171], v[204:207], v[124:127]
	v_mfma_f32_16x16x32_bf16 v[120:123], v[176:179], v[204:207], v[120:123]
	v_mfma_f32_16x16x32_bf16 v[112:115], v[168:171], v[212:215], v[112:115]
	v_mfma_f32_16x16x32_bf16 v[104:107], v[176:179], v[212:215], v[104:107]
	v_mfma_f32_16x16x32_bf16 v[92:95], v[168:171], v[220:223], v[92:95]
	v_mfma_f32_16x16x32_bf16 v[88:91], v[176:179], v[220:223], v[88:91]
	v_mfma_f32_16x16x32_bf16 v[84:87], v[168:171], v[228:231], v[84:87]
	v_mfma_f32_16x16x32_bf16 v[80:83], v[176:179], v[228:231], v[80:83]
	s_setprio 0
	s_setprio 1
	v_mfma_f32_16x16x32_bf16 v[116:119], v[180:183], v[200:203], v[116:119]
	v_mfma_f32_16x16x32_bf16 v[108:111], v[192:195], v[200:203], v[108:111]
	v_mfma_f32_16x16x32_bf16 v[100:103], v[180:183], v[208:211], v[100:103]
	v_mfma_f32_16x16x32_bf16 v[96:99], v[192:195], v[208:211], v[96:99]
	v_mfma_f32_16x16x32_bf16 v[76:79], v[180:183], v[216:219], v[76:79]
	v_mfma_f32_16x16x32_bf16 v[72:75], v[192:195], v[216:219], v[72:75]
	v_mfma_f32_16x16x32_bf16 v[68:71], v[180:183], v[224:227], v[68:71]
	v_mfma_f32_16x16x32_bf16 v[64:67], v[192:195], v[224:227], v[64:67]
	v_mfma_f32_16x16x32_bf16 v[116:119], v[188:191], v[204:207], v[116:119]
	v_mfma_f32_16x16x32_bf16 v[108:111], v[196:199], v[204:207], v[108:111]
	v_mfma_f32_16x16x32_bf16 v[100:103], v[188:191], v[212:215], v[100:103]
	v_mfma_f32_16x16x32_bf16 v[96:99], v[196:199], v[212:215], v[96:99]
	v_mfma_f32_16x16x32_bf16 v[76:79], v[188:191], v[220:223], v[76:79]
	v_mfma_f32_16x16x32_bf16 v[72:75], v[196:199], v[220:223], v[72:75]
	v_mfma_f32_16x16x32_bf16 v[68:71], v[188:191], v[228:231], v[68:71]
	v_mfma_f32_16x16x32_bf16 v[64:67], v[196:199], v[228:231], v[64:67]
	s_setprio 0
	s_barrier
	s_add_i32 s50, s48, s33
	v_lshl_add_u64 v[232:233], v[158:159], 0, v[134:135]
	s_mov_b32 m0, s50
	ds_read_b128 v[200:203], v157 offset:16384
	ds_read_b128 v[204:207], v157 offset:17408
	ds_read_b128 v[208:211], v157 offset:18432
	ds_read_b128 v[212:215], v157 offset:19456
	ds_read_b128 v[216:219], v157 offset:20480
	ds_read_b128 v[220:223], v157 offset:21504
	ds_read_b128 v[224:227], v157 offset:22528
	ds_read_b128 v[228:231], v157 offset:23552
	global_load_lds_dwordx4 v[232:233], off
	v_lshl_add_u64 v[236:237], v[158:159], 0, v[130:131]
	s_add_i32 m0, s50, 0x2000
	v_lshl_add_u64 v[238:239], v[158:159], 0, s[8:9]
	s_add_i32 s50, s49, s33
	global_load_lds_dwordx4 v[236:237], off
	v_lshl_add_u64 v[240:241], v[238:239], 0, v[134:135]
	s_mov_b32 m0, s50
	v_lshl_add_u64 v[238:239], v[238:239], 0, v[130:131]
	global_load_lds_dwordx4 v[240:241], off
	s_add_i32 m0, s50, 0x2000
	v_lshl_add_u64 v[240:241], s[36:37], 0, v[132:133]
	global_load_lds_dwordx4 v[238:239], off
	v_lshl_add_u64 v[238:239], s[36:37], 0, v[136:137]
	s_mov_b32 m0, s29
	s_nop 0
	global_load_lds_dwordx4 v[238:239], off
	s_mov_b32 m0, s31
	s_nop 0
	global_load_lds_dwordx4 v[240:241], off
	s_waitcnt vmcnt(8)
	s_waitcnt lgkmcnt(0)
	s_barrier
	s_setprio 1
	s_waitcnt lgkmcnt(0)
	s_cmp_eq_u32 s40, 2
	s_cbranch_scc0 .Lm0_kfull_a
	s_cmp_eq_u32 s46, 0x100
	s_cbranch_scc1 .Lm0_kskip_a
.Lm0_kfull_a:
	v_mfma_f32_16x16x32_bf16 v[60:63], v[164:167], v[200:203], v[60:63]
	v_mfma_f32_16x16x32_bf16 v[56:59], v[172:175], v[200:203], v[56:59]
	v_mfma_f32_16x16x32_bf16 v[52:55], v[164:167], v[208:211], v[52:55]
	v_mfma_f32_16x16x32_bf16 v[48:51], v[172:175], v[208:211], v[48:51]
	v_mfma_f32_16x16x32_bf16 v[28:31], v[164:167], v[216:219], v[28:31]
	v_mfma_f32_16x16x32_bf16 v[24:27], v[172:175], v[216:219], v[24:27]
	v_mfma_f32_16x16x32_bf16 v[20:23], v[164:167], v[224:227], v[20:23]
	v_mfma_f32_16x16x32_bf16 v[16:19], v[172:175], v[224:227], v[16:19]
	v_mfma_f32_16x16x32_bf16 v[60:63], v[168:171], v[204:207], v[60:63]
	v_mfma_f32_16x16x32_bf16 v[56:59], v[176:179], v[204:207], v[56:59]
	v_mfma_f32_16x16x32_bf16 v[52:55], v[168:171], v[212:215], v[52:55]
	v_mfma_f32_16x16x32_bf16 v[48:51], v[176:179], v[212:215], v[48:51]
	v_mfma_f32_16x16x32_bf16 v[28:31], v[168:171], v[220:223], v[28:31]
	v_mfma_f32_16x16x32_bf16 v[24:27], v[176:179], v[220:223], v[24:27]
	v_mfma_f32_16x16x32_bf16 v[20:23], v[168:171], v[228:231], v[20:23]
	v_mfma_f32_16x16x32_bf16 v[16:19], v[176:179], v[228:231], v[16:19]
	s_setprio 0
	s_setprio 1
	v_mfma_f32_16x16x32_bf16 v[44:47], v[180:183], v[200:203], v[44:47]
	v_mfma_f32_16x16x32_bf16 v[40:43], v[192:195], v[200:203], v[40:43]
	v_mfma_f32_16x16x32_bf16 v[36:39], v[180:183], v[208:211], v[36:39]
	v_mfma_f32_16x16x32_bf16 v[32:35], v[192:195], v[208:211], v[32:35]
	v_mfma_f32_16x16x32_bf16 v[12:15], v[180:183], v[216:219], v[12:15]
	v_mfma_f32_16x16x32_bf16 v[8:11], v[192:195], v[216:219], v[8:11]
	v_mfma_f32_16x16x32_bf16 v[4:7], v[180:183], v[224:227], v[4:7]
	v_mfma_f32_16x16x32_bf16 v[0:3], v[192:195], v[224:227], v[0:3]
	v_mfma_f32_16x16x32_bf16 v[44:47], v[188:191], v[204:207], v[44:47]
	v_mfma_f32_16x16x32_bf16 v[40:43], v[196:199], v[204:207], v[40:43]
	v_mfma_f32_16x16x32_bf16 v[36:39], v[188:191], v[212:215], v[36:39]
	v_mfma_f32_16x16x32_bf16 v[32:35], v[196:199], v[212:215], v[32:35]
	v_mfma_f32_16x16x32_bf16 v[12:15], v[188:191], v[220:223], v[12:15]
	v_mfma_f32_16x16x32_bf16 v[8:11], v[196:199], v[220:223], v[8:11]
	v_mfma_f32_16x16x32_bf16 v[4:7], v[188:191], v[228:231], v[4:7]
	v_mfma_f32_16x16x32_bf16 v[0:3], v[196:199], v[228:231], v[0:3]
.Lm0_kskip_a:
	s_setprio 0
	s_barrier
	s_add_i32 s50, 0, 0x18000
	s_add_i32 s51, 0, 0x1c000
	v_add_u32_e32 v176, s50, v154
	v_add_u32_e32 v196, s51, v154
	ds_read_b128 v[164:167], v176
	ds_read_b128 v[168:171], v176 offset:1024
	ds_read_b128 v[172:175], v176 offset:2048
	ds_read_b128 v[176:179], v176 offset:3072
	ds_read_b128 v[180:183], v196
	ds_read_b128 v[188:191], v196 offset:1024
	ds_read_b128 v[192:195], v196 offset:2048
	ds_read_b128 v[196:199], v196 offset:3072
	s_add_u32 s36, s36, 0x40000
	s_addc_u32 s37, s37, 0
	s_mov_b32 m0, s38
	v_lshl_add_u64 v[242:243], s[36:37], 0, v[136:137]
	ds_read_b128 v[200:203], v157 offset:32768
	ds_read_b128 v[204:207], v157 offset:33792
	ds_read_b128 v[208:211], v157 offset:34816
	ds_read_b128 v[212:215], v157 offset:35840
	ds_read_b128 v[216:219], v157 offset:36864
	ds_read_b128 v[220:223], v157 offset:37888
	ds_read_b128 v[224:227], v157 offset:38912
	ds_read_b128 v[228:231], v157 offset:39936
	global_load_lds_dwordx4 v[242:243], off
	v_lshl_add_u64 v[242:243], s[36:37], 0, v[132:133]
	s_mov_b32 m0, s39
	s_nop 0
	global_load_lds_dwordx4 v[242:243], off
	s_waitcnt vmcnt(8)
	s_waitcnt lgkmcnt(0)
	s_barrier
	s_setprio 1
	s_waitcnt lgkmcnt(0)
	v_mfma_f32_16x16x32_bf16 v[124:127], v[164:167], v[200:203], v[124:127]
	v_mfma_f32_16x16x32_bf16 v[120:123], v[172:175], v[200:203], v[120:123]
	v_mfma_f32_16x16x32_bf16 v[112:115], v[164:167], v[208:211], v[112:115]
	v_mfma_f32_16x16x32_bf16 v[104:107], v[172:175], v[208:211], v[104:107]
	v_mfma_f32_16x16x32_bf16 v[92:95], v[164:167], v[216:219], v[92:95]
	v_mfma_f32_16x16x32_bf16 v[88:91], v[172:175], v[216:219], v[88:91]
	v_mfma_f32_16x16x32_bf16 v[84:87], v[164:167], v[224:227], v[84:87]
	v_mfma_f32_16x16x32_bf16 v[80:83], v[172:175], v[224:227], v[80:83]
	v_mfma_f32_16x16x32_bf16 v[124:127], v[168:171], v[204:207], v[124:127]
	v_mfma_f32_16x16x32_bf16 v[120:123], v[176:179], v[204:207], v[120:123]
	v_mfma_f32_16x16x32_bf16 v[112:115], v[168:171], v[212:215], v[112:115]
	v_mfma_f32_16x16x32_bf16 v[104:107], v[176:179], v[212:215], v[104:107]
	v_mfma_f32_16x16x32_bf16 v[92:95], v[168:171], v[220:223], v[92:95]
	v_mfma_f32_16x16x32_bf16 v[88:91], v[176:179], v[220:223], v[88:91]
	v_mfma_f32_16x16x32_bf16 v[84:87], v[168:171], v[228:231], v[84:87]
	v_mfma_f32_16x16x32_bf16 v[80:83], v[176:179], v[228:231], v[80:83]
	s_setprio 0
	s_setprio 1
	v_mfma_f32_16x16x32_bf16 v[116:119], v[180:183], v[200:203], v[116:119]
	v_mfma_f32_16x16x32_bf16 v[108:111], v[192:195], v[200:203], v[108:111]
	v_mfma_f32_16x16x32_bf16 v[100:103], v[180:183], v[208:211], v[100:103]
	v_mfma_f32_16x16x32_bf16 v[96:99], v[192:195], v[208:211], v[96:99]
	v_mfma_f32_16x16x32_bf16 v[76:79], v[180:183], v[216:219], v[76:79]
	v_mfma_f32_16x16x32_bf16 v[72:75], v[192:195], v[216:219], v[72:75]
	v_mfma_f32_16x16x32_bf16 v[68:71], v[180:183], v[224:227], v[68:71]
	v_mfma_f32_16x16x32_bf16 v[64:67], v[192:195], v[224:227], v[64:67]
	v_mfma_f32_16x16x32_bf16 v[116:119], v[188:191], v[204:207], v[116:119]
	v_mfma_f32_16x16x32_bf16 v[108:111], v[196:199], v[204:207], v[108:111]
	v_mfma_f32_16x16x32_bf16 v[100:103], v[188:191], v[212:215], v[100:103]
	v_mfma_f32_16x16x32_bf16 v[96:99], v[196:199], v[212:215], v[96:99]
	v_mfma_f32_16x16x32_bf16 v[76:79], v[188:191], v[220:223], v[76:79]
	v_mfma_f32_16x16x32_bf16 v[72:75], v[196:199], v[220:223], v[72:75]
	v_mfma_f32_16x16x32_bf16 v[68:71], v[188:191], v[228:231], v[68:71]
	v_mfma_f32_16x16x32_bf16 v[64:67], v[196:199], v[228:231], v[64:67]
	s_setprio 0
	s_barrier
	s_add_i32 s36, s50, s33
	v_lshl_add_u64 v[232:233], v[232:233], 0, s[12:13]
	s_mov_b32 m0, s36
	ds_read_b128 v[200:203], v157 offset:49152
	ds_read_b128 v[204:207], v157 offset:50176
	ds_read_b128 v[208:211], v157 offset:51200
	ds_read_b128 v[212:215], v157 offset:52224
	ds_read_b128 v[216:219], v157 offset:53248
	ds_read_b128 v[220:223], v157 offset:54272
	ds_read_b128 v[224:227], v157 offset:55296
	ds_read_b128 v[228:231], v157 offset:56320
	global_load_lds_dwordx4 v[232:233], off
	v_lshl_add_u64 v[232:233], v[236:237], 0, s[12:13]
	s_add_i32 m0, s36, 0x2000
	v_lshl_add_u64 v[158:159], v[158:159], 0, s[14:15]
	s_add_i32 s36, s51, s33
	global_load_lds_dwordx4 v[232:233], off
	v_lshl_add_u64 v[232:233], v[158:159], 0, v[134:135]
	s_mov_b32 m0, s36
	v_lshl_add_u64 v[158:159], v[158:159], 0, v[130:131]
	global_load_lds_dwordx4 v[232:233], off
	s_add_i32 m0, s36, 0x2000
	s_nop 0
	global_load_lds_dwordx4 v[158:159], off
	v_lshl_add_u64 v[158:159], v[238:239], 0, s[12:13]
	s_mov_b32 m0, s41
	s_nop 0
	global_load_lds_dwordx4 v[158:159], off
	v_lshl_add_u64 v[158:159], v[240:241], 0, s[12:13]
	s_mov_b32 m0, s42
	s_nop 0
	global_load_lds_dwordx4 v[158:159], off
	s_waitcnt vmcnt(8)
	s_waitcnt lgkmcnt(0)
	s_barrier
	s_setprio 1
	s_waitcnt lgkmcnt(0)
	s_cmp_eq_u32 s40, 2
	s_cbranch_scc0 .Lm0_kfull_b
	s_cmp_eq_u32 s46, 0x100
	s_cbranch_scc1 .Lm0_kskip_b

.Lm0_kskip_b:
	s_setprio 0
	s_barrier
	s_add_i32 s23, s23, 2
	s_add_u32 s34, s34, 0x100
	s_addc_u32 s35, s35, 0
	s_cmp_gt_u32 s23, 13
	v_lshl_add_u64 v[150:151], v[150:151], 0, s[18:19]
	s_cbranch_scc0 .LBB0_872
	s_and_b64 vcc, exec, s[16:17]
	s_cbranch_vccz .LBB0_875
	s_barrier
.LBB0_875:
	s_lshl_b32 s21, s30, 8
	v_mov_b32_e32 v148, v153
	v_mov_b32_e32 v149, v152
	s_add_i32 s21, s21, s43
	s_cmp_eq_u32 s40, 2
	s_cbranch_scc0 .Lm0_rb_skip
	s_cmp_eq_u32 s46, 0x100
	s_cbranch_scc0 .Lm0_rb_skip
	s_and_b32 s98, s2, 1
	s_lshl_b32 s98, s98, 7
	s_add_i32 s21, s21, s98
.Lm0_rb_skip:
	s_andn2_b64 vcc, exec, s[4:5]
	v_add_u32_e32 v150, s21, v149
	s_lshl_b32 s21, s28, 8
	s_or_b32 s21, s21, s44
	v_lshl_add_u32 v148, v148, 3, s21
	v_ashrrev_i32_e32 v151, 31, v150
	v_ashrrev_i32_e32 v149, 31, v148
	v_lshlrev_b64 v[158:159], 12, v[150:151]
	v_lshl_add_u64 v[158:159], v[162:163], 0, v[158:159]
	v_lshlrev_b64 v[148:149], 1, v[148:149]
	v_lshl_add_u64 v[158:159], v[158:159], 0, v[148:149]
	global_load_dwordx4 v[164:167], v[158:159], off
	global_load_dwordx4 v[168:171], v[158:159], off offset:256
	v_add_u32_e32 v158, 16, v150
	v_ashrrev_i32_e32 v159, 31, v158
	v_lshlrev_b64 v[172:173], 12, v[158:159]
	v_lshl_add_u64 v[172:173], v[162:163], 0, v[172:173]
	v_lshl_add_u64 v[176:177], v[172:173], 0, v[148:149]
	global_load_dwordx4 v[172:175], v[176:177], off
	s_nop 0
	global_load_dwordx4 v[176:179], v[176:177], off offset:256
	v_lshlrev_b64 v[182:183], 11, v[150:151]
	v_lshlrev_b64 v[158:159], 11, v[158:159]
	v_add_u32_e32 v180, 32, v150
	v_lshl_add_u64 v[182:183], v[186:187], 0, v[182:183]
	v_lshl_add_u64 v[158:159], v[186:187], 0, v[158:159]
	v_lshl_add_u64 v[182:183], v[182:183], 0, v[148:149]
	v_lshl_add_u64 v[158:159], v[158:159], 0, v[148:149]
	v_ashrrev_i32_e32 v181, 31, v180
	s_mov_b64 s[4:5], -1
	s_waitcnt vmcnt(0)
	v_lshlrev_b32_e32 v188, 16, v164
	v_and_b32_e32 v189, 0xffff0000, v164
	v_lshlrev_b32_e32 v164, 16, v165
	v_and_b32_e32 v165, 0xffff0000, v165
	v_lshlrev_b32_e32 v192, 16, v168
	v_and_b32_e32 v193, 0xffff0000, v168
	v_lshlrev_b32_e32 v168, 16, v169
	v_and_b32_e32 v169, 0xffff0000, v169
	v_lshlrev_b32_e32 v194, 16, v170
	v_and_b32_e32 v195, 0xffff0000, v170
	v_lshlrev_b32_e32 v170, 16, v171
	v_and_b32_e32 v171, 0xffff0000, v171
	v_lshlrev_b32_e32 v190, 16, v166
	v_and_b32_e32 v191, 0xffff0000, v166
	v_lshlrev_b32_e32 v166, 16, v167
	v_and_b32_e32 v167, 0xffff0000, v167
	v_pk_mul_f32 v[126:127], v[126:127], v[164:165]
	v_pk_mul_f32 v[118:119], v[118:119], v[168:169]
	v_pk_mul_f32 v[164:165], v[110:111], v[170:171]
	v_lshlrev_b32_e32 v168, 16, v172
	v_and_b32_e32 v169, 0xffff0000, v172
	v_lshlrev_b32_e32 v170, 16, v173
	v_and_b32_e32 v171, 0xffff0000, v173
	v_lshlrev_b32_e32 v172, 16, v174
	v_and_b32_e32 v173, 0xffff0000, v174
	v_lshlrev_b32_e32 v174, 16, v175
	v_and_b32_e32 v175, 0xffff0000, v175
	v_pk_mul_f32 v[124:125], v[124:125], v[188:189]
	v_pk_mul_f32 v[122:123], v[122:123], v[166:167]
	v_pk_mul_f32 v[120:121], v[120:121], v[190:191]
	v_lshlrev_b32_e32 v188, 16, v176
	v_and_b32_e32 v189, 0xffff0000, v176
	v_lshlrev_b32_e32 v176, 16, v177
	v_and_b32_e32 v177, 0xffff0000, v177
	v_pk_mul_f32 v[114:115], v[114:115], v[170:171]
	v_pk_mul_f32 v[112:113], v[112:113], v[168:169]
	v_pk_mul_f32 v[106:107], v[106:107], v[174:175]
	v_pk_mul_f32 v[104:105], v[104:105], v[172:173]
	v_pk_mul_f32 v[116:117], v[116:117], v[192:193]
	v_pk_mul_f32 v[166:167], v[108:109], v[194:195]
	v_lshlrev_b32_e32 v190, 16, v178
	v_and_b32_e32 v191, 0xffff0000, v178
	v_lshlrev_b32_e32 v178, 16, v179
	v_and_b32_e32 v179, 0xffff0000, v179
	v_cvt_pk_bf16_f32 v108, v124, v125
	v_cvt_pk_bf16_f32 v109, v126, v127
	v_cvt_pk_bf16_f32 v110, v120, v121
	v_cvt_pk_bf16_f32 v111, v122, v123
	v_pk_mul_f32 v[120:121], v[102:103], v[176:177]
	v_pk_mul_f32 v[122:123], v[100:101], v[188:189]
	v_cvt_pk_bf16_f32 v100, v112, v113
	v_cvt_pk_bf16_f32 v101, v114, v115
	v_cvt_pk_bf16_f32 v102, v104, v105
	v_cvt_pk_bf16_f32 v103, v106, v107
	v_cvt_pk_bf16_f32 v116, v116, v117
	v_cvt_pk_bf16_f32 v117, v118, v119
	v_cvt_pk_bf16_f32 v118, v166, v167
	v_cvt_pk_bf16_f32 v119, v164, v165
	global_store_dwordx4 v[182:183], v[108:111], off
	global_store_dwordx4 v[182:183], v[116:119], off offset:256
	global_store_dwordx4 v[158:159], v[100:103], off
	v_pk_mul_f32 v[106:107], v[98:99], v[178:179]
	v_pk_mul_f32 v[98:99], v[96:97], v[190:191]
	v_lshlrev_b64 v[100:101], 12, v[180:181]
	v_lshl_add_u64 v[100:101], v[162:163], 0, v[100:101]
	v_cvt_pk_bf16_f32 v96, v122, v123
	v_cvt_pk_bf16_f32 v97, v120, v121
	v_cvt_pk_bf16_f32 v98, v98, v99
	v_cvt_pk_bf16_f32 v99, v106, v107
	v_add_u32_e32 v112, 48, v150
	v_lshl_add_u64 v[104:105], v[100:101], 0, v[148:149]
	global_store_dwordx4 v[158:159], v[96:99], off offset:256
	v_ashrrev_i32_e32 v113, 31, v112
	global_load_dwordx4 v[100:103], v[104:105], off
	global_load_dwordx4 v[96:99], v[104:105], off offset:256
	v_lshlrev_b64 v[104:105], 12, v[112:113]
	v_lshl_add_u64 v[104:105], v[162:163], 0, v[104:105]
	v_lshl_add_u64 v[108:109], v[104:105], 0, v[148:149]
	global_load_dwordx4 v[104:107], v[108:109], off
	s_nop 0
	global_load_dwordx4 v[108:111], v[108:109], off offset:256
	v_lshlrev_b64 v[114:115], 11, v[180:181]
	v_lshlrev_b64 v[112:113], 11, v[112:113]
	v_lshl_add_u64 v[114:115], v[186:187], 0, v[114:115]
	v_lshl_add_u64 v[112:113], v[186:187], 0, v[112:113]
	v_lshl_add_u64 v[114:115], v[114:115], 0, v[148:149]
	v_lshl_add_u64 v[112:113], v[112:113], 0, v[148:149]
	s_waitcnt vmcnt(3)
	v_lshlrev_b32_e32 v116, 16, v100
	v_and_b32_e32 v117, 0xffff0000, v100
	v_lshlrev_b32_e32 v100, 16, v101
	v_and_b32_e32 v101, 0xffff0000, v101
	v_lshlrev_b32_e32 v118, 16, v102
	v_and_b32_e32 v119, 0xffff0000, v102
	v_lshlrev_b32_e32 v102, 16, v103
	v_and_b32_e32 v103, 0xffff0000, v103
	s_waitcnt vmcnt(1)
	v_lshlrev_b32_e32 v124, 16, v104
	v_and_b32_e32 v125, 0xffff0000, v104
	v_lshlrev_b32_e32 v120, 16, v96
	v_and_b32_e32 v121, 0xffff0000, v96
	v_lshlrev_b32_e32 v96, 16, v97
	v_and_b32_e32 v97, 0xffff0000, v97
	v_lshlrev_b32_e32 v122, 16, v98
	v_and_b32_e32 v123, 0xffff0000, v98
	v_lshlrev_b32_e32 v98, 16, v99
	v_and_b32_e32 v99, 0xffff0000, v99
	v_lshlrev_b32_e32 v104, 16, v105
	v_and_b32_e32 v105, 0xffff0000, v105
	v_lshlrev_b32_e32 v126, 16, v106
	v_and_b32_e32 v127, 0xffff0000, v106
	v_lshlrev_b32_e32 v106, 16, v107
	v_and_b32_e32 v107, 0xffff0000, v107
	v_pk_mul_f32 v[94:95], v[94:95], v[100:101]
	v_pk_mul_f32 v[92:93], v[92:93], v[116:117]
	v_pk_mul_f32 v[90:91], v[90:91], v[102:103]
	v_pk_mul_f32 v[88:89], v[88:89], v[118:119]
	v_pk_mul_f32 v[84:85], v[84:85], v[124:125]
	v_pk_mul_f32 v[78:79], v[78:79], v[96:97]
	v_pk_mul_f32 v[76:77], v[76:77], v[120:121]
	v_pk_mul_f32 v[96:97], v[74:75], v[98:99]
	v_pk_mul_f32 v[98:99], v[72:73], v[122:123]
	v_pk_mul_f32 v[86:87], v[86:87], v[104:105]
	v_pk_mul_f32 v[100:101], v[82:83], v[106:107]
	v_pk_mul_f32 v[82:83], v[80:81], v[126:127]
	v_cvt_pk_bf16_f32 v72, v92, v93
	v_cvt_pk_bf16_f32 v73, v94, v95
	v_cvt_pk_bf16_f32 v74, v88, v89
	v_cvt_pk_bf16_f32 v75, v90, v91
	v_cvt_pk_bf16_f32 v80, v84, v85
	v_cvt_pk_bf16_f32 v76, v76, v77
	v_cvt_pk_bf16_f32 v77, v78, v79
	v_cvt_pk_bf16_f32 v78, v98, v99
	v_cvt_pk_bf16_f32 v79, v96, v97
	v_cvt_pk_bf16_f32 v81, v86, v87
	v_cvt_pk_bf16_f32 v82, v82, v83
	v_cvt_pk_bf16_f32 v83, v100, v101
	global_store_dwordx4 v[114:115], v[72:75], off
	global_store_dwordx4 v[114:115], v[76:79], off offset:256
	global_store_dwordx4 v[112:113], v[80:83], off
	s_waitcnt vmcnt(3)
	v_lshlrev_b32_e32 v158, 16, v108
	v_and_b32_e32 v159, 0xffff0000, v108
	v_add_u32_e32 v80, 0x80, v150
	v_lshlrev_b32_e32 v108, 16, v109
	v_and_b32_e32 v109, 0xffff0000, v109
	v_lshlrev_b32_e32 v164, 16, v110
	v_and_b32_e32 v165, 0xffff0000, v110
	v_lshlrev_b32_e32 v110, 16, v111
	v_and_b32_e32 v111, 0xffff0000, v111
	v_ashrrev_i32_e32 v81, 31, v80
	v_add_u32_e32 v82, 0x90, v150
	v_pk_mul_f32 v[72:73], v[70:71], v[108:109]
	v_pk_mul_f32 v[74:75], v[68:69], v[158:159]
	v_lshlrev_b64 v[68:69], 12, v[80:81]
	v_pk_mul_f32 v[78:79], v[66:67], v[110:111]
	v_pk_mul_f32 v[66:67], v[64:65], v[164:165]
	v_ashrrev_i32_e32 v83, 31, v82
	v_lshl_add_u64 v[68:69], v[162:163], 0, v[68:69]
	v_cvt_pk_bf16_f32 v64, v74, v75
	v_cvt_pk_bf16_f32 v65, v72, v73
	v_cvt_pk_bf16_f32 v66, v66, v67
	v_cvt_pk_bf16_f32 v67, v78, v79
	v_lshlrev_b64 v[72:73], 12, v[82:83]
	v_lshl_add_u64 v[76:77], v[68:69], 0, v[148:149]
	global_store_dwordx4 v[112:113], v[64:67], off offset:256
	s_cmp_eq_u32 s40, 2
	s_cbranch_scc0 .Lm0_epi_full
	s_cmp_eq_u32 s46, 0x100
	s_cbranch_scc1 .Lm0_epi_end
.Lm0_epi_full:
	v_lshl_add_u64 v[72:73], v[162:163], 0, v[72:73]
	global_load_dwordx4 v[68:71], v[76:77], off
	global_load_dwordx4 v[64:67], v[76:77], off offset:256
	v_lshl_add_u64 v[76:77], v[72:73], 0, v[148:149]
	global_load_dwordx4 v[72:75], v[76:77], off
	s_nop 0
	global_load_dwordx4 v[76:79], v[76:77], off offset:256
	v_lshlrev_b64 v[80:81], 11, v[80:81]
	v_lshlrev_b64 v[82:83], 11, v[82:83]
	v_lshl_add_u64 v[80:81], v[186:187], 0, v[80:81]
	v_lshl_add_u64 v[82:83], v[186:187], 0, v[82:83]
	v_lshl_add_u64 v[80:81], v[80:81], 0, v[148:149]
	v_lshl_add_u64 v[82:83], v[82:83], 0, v[148:149]
	s_waitcnt vmcnt(3)
	v_lshlrev_b32_e32 v84, 16, v68
	v_and_b32_e32 v85, 0xffff0000, v68
	v_lshlrev_b32_e32 v68, 16, v69
	v_and_b32_e32 v69, 0xffff0000, v69
	v_lshlrev_b32_e32 v86, 16, v70
	v_and_b32_e32 v87, 0xffff0000, v70
	v_lshlrev_b32_e32 v70, 16, v71
	v_and_b32_e32 v71, 0xffff0000, v71
	s_waitcnt vmcnt(1)
	v_lshlrev_b32_e32 v92, 16, v72
	v_and_b32_e32 v93, 0xffff0000, v72
	v_lshlrev_b32_e32 v88, 16, v64
	v_and_b32_e32 v89, 0xffff0000, v64
	v_lshlrev_b32_e32 v64, 16, v65
	v_and_b32_e32 v65, 0xffff0000, v65
	v_lshlrev_b32_e32 v90, 16, v66
	v_and_b32_e32 v91, 0xffff0000, v66
	v_lshlrev_b32_e32 v66, 16, v67
	v_and_b32_e32 v67, 0xffff0000, v67
	v_lshlrev_b32_e32 v72, 16, v73
	v_and_b32_e32 v73, 0xffff0000, v73
	v_lshlrev_b32_e32 v94, 16, v74
	v_and_b32_e32 v95, 0xffff0000, v74
	v_lshlrev_b32_e32 v74, 16, v75
	v_and_b32_e32 v75, 0xffff0000, v75
	v_pk_mul_f32 v[62:63], v[62:63], v[68:69]
	v_pk_mul_f32 v[60:61], v[60:61], v[84:85]
	v_pk_mul_f32 v[58:59], v[58:59], v[70:71]
	v_pk_mul_f32 v[56:57], v[56:57], v[86:87]
	v_pk_mul_f32 v[52:53], v[52:53], v[92:93]
	v_pk_mul_f32 v[46:47], v[46:47], v[64:65]
	v_pk_mul_f32 v[44:45], v[44:45], v[88:89]
	v_pk_mul_f32 v[64:65], v[42:43], v[66:67]
	v_pk_mul_f32 v[66:67], v[40:41], v[90:91]
	v_pk_mul_f32 v[54:55], v[54:55], v[72:73]
	v_pk_mul_f32 v[68:69], v[50:51], v[74:75]
	v_pk_mul_f32 v[50:51], v[48:49], v[94:95]
	v_cvt_pk_bf16_f32 v40, v60, v61
	v_cvt_pk_bf16_f32 v41, v62, v63
	v_cvt_pk_bf16_f32 v42, v56, v57
	v_cvt_pk_bf16_f32 v43, v58, v59
	v_cvt_pk_bf16_f32 v48, v52, v53
	v_cvt_pk_bf16_f32 v44, v44, v45
	v_cvt_pk_bf16_f32 v45, v46, v47
	v_cvt_pk_bf16_f32 v46, v66, v67
	v_cvt_pk_bf16_f32 v47, v64, v65
	v_cvt_pk_bf16_f32 v49, v54, v55
	v_cvt_pk_bf16_f32 v50, v50, v51
	v_cvt_pk_bf16_f32 v51, v68, v69
	global_store_dwordx4 v[80:81], v[40:43], off
	global_store_dwordx4 v[80:81], v[44:47], off offset:256
	global_store_dwordx4 v[82:83], v[48:51], off
	s_waitcnt vmcnt(3)
	v_lshlrev_b32_e32 v96, 16, v76
	v_and_b32_e32 v97, 0xffff0000, v76
	v_add_u32_e32 v48, 0xa0, v150
	v_lshlrev_b32_e32 v76, 16, v77
	v_and_b32_e32 v77, 0xffff0000, v77
	v_lshlrev_b32_e32 v40, 16, v78
	v_and_b32_e32 v41, 0xffff0000, v78
	v_lshlrev_b32_e32 v42, 16, v79
	v_and_b32_e32 v43, 0xffff0000, v79
	v_ashrrev_i32_e32 v49, 31, v48
	v_pk_mul_f32 v[44:45], v[38:39], v[76:77]
	v_pk_mul_f32 v[46:47], v[36:37], v[96:97]
	v_lshlrev_b64 v[36:37], 12, v[48:49]
	v_pk_mul_f32 v[42:43], v[34:35], v[42:43]
	v_pk_mul_f32 v[34:35], v[32:33], v[40:41]
	v_lshl_add_u64 v[36:37], v[162:163], 0, v[36:37]
	v_cvt_pk_bf16_f32 v32, v46, v47
	v_cvt_pk_bf16_f32 v33, v44, v45
	v_cvt_pk_bf16_f32 v34, v34, v35
	v_cvt_pk_bf16_f32 v35, v42, v43
	v_lshl_add_u64 v[50:51], v[36:37], 0, v[148:149]
	global_store_dwordx4 v[82:83], v[32:35], off offset:256
	global_load_dwordx4 v[36:39], v[50:51], off
	v_lshlrev_b64 v[48:49], 11, v[48:49]
	global_load_dwordx4 v[32:35], v[50:51], off offset:256
	v_add_u32_e32 v50, 0xb0, v150
	v_ashrrev_i32_e32 v51, 31, v50
	v_lshlrev_b64 v[40:41], 12, v[50:51]
	v_lshl_add_u64 v[40:41], v[162:163], 0, v[40:41]
	v_lshl_add_u64 v[44:45], v[40:41], 0, v[148:149]
	global_load_dwordx4 v[40:43], v[44:45], off
	s_nop 0
	global_load_dwordx4 v[44:47], v[44:45], off offset:256
	v_lshlrev_b64 v[50:51], 11, v[50:51]
	v_lshl_add_u64 v[48:49], v[186:187], 0, v[48:49]
	v_lshl_add_u64 v[50:51], v[186:187], 0, v[50:51]
	v_lshl_add_u64 v[48:49], v[48:49], 0, v[148:149]
	v_lshl_add_u64 v[50:51], v[50:51], 0, v[148:149]
	s_waitcnt vmcnt(3)
	v_lshlrev_b32_e32 v52, 16, v36
	v_and_b32_e32 v53, 0xffff0000, v36
	v_lshlrev_b32_e32 v36, 16, v37
	v_and_b32_e32 v37, 0xffff0000, v37
	v_lshlrev_b32_e32 v54, 16, v38
	v_and_b32_e32 v55, 0xffff0000, v38
	v_lshlrev_b32_e32 v38, 16, v39
	v_and_b32_e32 v39, 0xffff0000, v39
	s_waitcnt vmcnt(2)
	v_lshlrev_b32_e32 v56, 16, v32
	v_and_b32_e32 v57, 0xffff0000, v32
	v_lshlrev_b32_e32 v32, 16, v33
	v_and_b32_e32 v33, 0xffff0000, v33
	v_lshlrev_b32_e32 v58, 16, v34
	v_and_b32_e32 v59, 0xffff0000, v34
	v_lshlrev_b32_e32 v34, 16, v35
	v_and_b32_e32 v35, 0xffff0000, v35
	s_waitcnt vmcnt(1)
	v_lshlrev_b32_e32 v60, 16, v40
	v_and_b32_e32 v61, 0xffff0000, v40
	v_lshlrev_b32_e32 v40, 16, v41
	v_and_b32_e32 v41, 0xffff0000, v41
	v_lshlrev_b32_e32 v62, 16, v42
	v_and_b32_e32 v63, 0xffff0000, v42
	v_lshlrev_b32_e32 v42, 16, v43
	v_and_b32_e32 v43, 0xffff0000, v43
	v_pk_mul_f32 v[30:31], v[30:31], v[36:37]
	v_pk_mul_f32 v[28:29], v[28:29], v[52:53]
	v_pk_mul_f32 v[26:27], v[26:27], v[38:39]
	v_pk_mul_f32 v[24:25], v[24:25], v[54:55]
	v_pk_mul_f32 v[14:15], v[14:15], v[32:33]
	v_pk_mul_f32 v[12:13], v[12:13], v[56:57]
	v_pk_mul_f32 v[32:33], v[10:11], v[34:35]
	v_pk_mul_f32 v[34:35], v[8:9], v[58:59]
	v_pk_mul_f32 v[22:23], v[22:23], v[40:41]
	v_pk_mul_f32 v[20:21], v[20:21], v[60:61]
	v_pk_mul_f32 v[36:37], v[18:19], v[42:43]
	v_pk_mul_f32 v[18:19], v[16:17], v[62:63]
	v_cvt_pk_bf16_f32 v8, v28, v29
	v_cvt_pk_bf16_f32 v9, v30, v31
	v_cvt_pk_bf16_f32 v10, v24, v25
	v_cvt_pk_bf16_f32 v11, v26, v27
	v_cvt_pk_bf16_f32 v12, v12, v13
	v_cvt_pk_bf16_f32 v13, v14, v15
	v_cvt_pk_bf16_f32 v14, v34, v35
	v_cvt_pk_bf16_f32 v15, v32, v33
	v_cvt_pk_bf16_f32 v16, v20, v21
	v_cvt_pk_bf16_f32 v17, v22, v23
	v_cvt_pk_bf16_f32 v18, v18, v19
	v_cvt_pk_bf16_f32 v19, v36, v37
	global_store_dwordx4 v[48:49], v[8:11], off
	global_store_dwordx4 v[48:49], v[12:15], off offset:256
	global_store_dwordx4 v[50:51], v[16:19], off
	s_waitcnt vmcnt(3)
	v_lshlrev_b32_e32 v8, 16, v44
	v_and_b32_e32 v9, 0xffff0000, v44
	v_lshlrev_b32_e32 v10, 16, v45
	v_and_b32_e32 v11, 0xffff0000, v45
	v_lshlrev_b32_e32 v12, 16, v46
	v_and_b32_e32 v13, 0xffff0000, v46
	v_lshlrev_b32_e32 v14, 16, v47
	v_and_b32_e32 v15, 0xffff0000, v47
	v_pk_mul_f32 v[6:7], v[6:7], v[10:11]
	v_pk_mul_f32 v[4:5], v[4:5], v[8:9]
	v_pk_mul_f32 v[8:9], v[2:3], v[14:15]
	v_pk_mul_f32 v[2:3], v[0:1], v[12:13]
	v_cvt_pk_bf16_f32 v0, v4, v5
	v_cvt_pk_bf16_f32 v1, v6, v7
	v_cvt_pk_bf16_f32 v2, v2, v3
	v_cvt_pk_bf16_f32 v3, v8, v9
	global_store_dwordx4 v[50:51], v[0:3], off offset:256
.Lm0_epi_end:
	s_cbranch_vccnz .LBB0_868
	s_andn2_b64 vcc, exec, s[10:11]
	s_cbranch_vccnz .LBB0_867
	s_barrier
	s_branch .LBB0_867

.LBB0_885:
	s_add_i32 s42, s42, 1
	s_mul_i32 s6, s42, s47
	s_mul_hi_u32 s7, s42, s48
	s_add_i32 s7, s7, s6
	s_mul_i32 s6, s42, s48
	s_add_u32 s26, s6, s2
	s_addc_u32 s27, s7, s49
	s_cmp_eq_u32 s42, 1
	s_cbranch_scc0 .Lm1_enum_skip
	s_cmp_eq_u32 s48, 0x100
	s_cbranch_scc0 .Lm1_enum_skip
	s_lshr_b32 s26, s2, 1
	s_add_u32 s26, s26, 0x100
	s_mov_b32 s27, 0
.Lm1_enum_skip:
	v_cmp_gt_i64_e32 vcc, s[26:27], v[144:145]
	v_cmp_lt_i64_e64 s[6:7], s[26:27], v[142:143]
	s_cbranch_vccnz .LBB0_887
	s_mul_hi_i32 s20, s26, 0x2aaaaaab
	s_lshr_b32 s21, s20, 31
	s_ashr_i32 s20, s20, 6
	s_add_i32 s20, s20, s21
	s_mul_i32 s21, s20, 0xfffffe80
	s_add_i32 s21, s21, s26
	s_ashr_i32 s22, s21, 31
	s_lshr_b32 s22, s22, 29
	s_add_i32 s22, s21, s22
	s_ashr_i32 s23, s22, 3
	s_and_b32 s22, s22, -8
	s_sub_i32 s21, s21, s22
	s_cmp_lt_i32 s21, 0
	s_cselect_b32 s22, 49, 48
	s_mul_i32 s21, s22, s21
	s_add_i32 s21, s21, s23
	s_ashr_i32 s22, s21, 31
	s_lshr_b32 s22, s22, 27
	s_add_i32 s22, s21, s22
	s_ashr_i32 s23, s22, 5
	s_lshl_b32 s23, s23, 3
	s_sub_i32 s24, 0x60, s23
	s_min_i32 s24, s24, 8
	s_abs_i32 s25, s24
	v_cvt_f32_u32_e32 v2, s25
	s_sub_i32 s27, 0, s25
	s_andn2_b32 s22, s22, 31
	s_sub_i32 s21, s21, s22
	v_rcp_iflag_f32_e32 v2, v2
	s_abs_i32 s22, s21
	s_xor_b32 s26, s21, s24
	s_ashr_i32 s26, s26, 31
	v_mul_f32_e32 v2, 0x4f7ffffe, v2
	v_cvt_u32_f32_e32 v2, v2
	s_nop 0
	v_readfirstlane_b32 s36, v2
	s_mul_i32 s27, s27, s36
	s_mul_hi_u32 s27, s36, s27
	s_add_i32 s36, s36, s27
	s_mul_hi_u32 s27, s22, s36
	s_mul_i32 s36, s27, s25
	s_sub_i32 s22, s22, s36
	s_add_i32 s37, s27, 1
	s_sub_i32 s36, s22, s25
	s_cmp_ge_u32 s22, s25
	s_cselect_b32 s27, s37, s27
	s_cselect_b32 s22, s36, s22
	s_add_i32 s36, s27, 1
	s_cmp_ge_u32 s22, s25
	s_cselect_b32 s22, s36, s27
	s_xor_b32 s22, s22, s26
	s_sub_i32 s22, s22, s26
	s_mul_i32 s24, s22, s24
	s_sub_i32 s21, s21, s24
	s_add_i32 s24, s21, s23
.LBB0_887:
	s_ashr_i32 s25, s24, 31
	s_lshl_b64 s[26:27], s[24:25], 19
	s_cmp_eq_u32 s42, 1
	s_cbranch_scc0 .Lm1_a_skip
	s_cmp_eq_u32 s48, 0x100
	s_cbranch_scc0 .Lm1_a_skip
	s_and_b32 s98, s2, 1
	s_lshl_b32 s98, s98, 18
	s_or_b32 s26, s26, s98
.Lm1_a_skip:
	s_add_u32 s23, s38, s26
	s_addc_u32 s25, s39, s27
	s_ashr_i32 s21, s20, 31
	s_lshl_b64 s[36:37], s[20:21], 11
	s_add_u32 s26, s23, s36
	s_addc_u32 s27, s25, s37
	s_and_b64 s[54:55], s[6:7], exec
	s_cselect_b32 s21, s27, s35
	s_cselect_b32 s25, s26, s34
	s_ashr_i32 s23, s22, 31
	s_lshl_b64 s[54:55], s[22:23], 19
	v_lshl_add_u64 v[2:3], v[128:129], 0, s[54:55]
	v_lshl_add_u64 v[146:147], v[2:3], 0, s[36:37]
	v_cndmask_b32_e64 v148, v0, v146, s[6:7]
	s_add_u32 s34, s34, 0x40080
	v_lshl_add_u64 v[150:151], v[0:1], 0, s[18:19]
	v_mov_b32_e32 v0, 0
	v_cndmask_b32_e64 v149, v1, v147, s[6:7]
	s_addc_u32 s35, s35, 0
	s_mov_b32 s23, -2
	v_mov_b32_e32 v1, v0
	v_mov_b32_e32 v2, v0
	v_mov_b32_e32 v3, v0
	v_mov_b32_e32 v4, v0
	v_mov_b32_e32 v5, v0
	v_mov_b32_e32 v6, v0
	v_mov_b32_e32 v7, v0
	v_mov_b32_e32 v16, v0
	v_mov_b32_e32 v17, v0
	s_waitcnt vmcnt(0)
	v_mov_b32_e32 v18, v0
	v_mov_b32_e32 v19, v0
	v_mov_b32_e32 v20, v0
	v_mov_b32_e32 v21, v0
	v_mov_b32_e32 v22, v0
	v_mov_b32_e32 v23, v0
	v_mov_b32_e32 v32, v0
	v_mov_b32_e32 v33, v0
	v_mov_b32_e32 v34, v0
	v_mov_b32_e32 v35, v0
	v_mov_b32_e32 v36, v0
	v_mov_b32_e32 v37, v0
	v_mov_b32_e32 v38, v0
	v_mov_b32_e32 v39, v0
	v_mov_b32_e32 v48, v0
	v_mov_b32_e32 v49, v0
	v_mov_b32_e32 v50, v0
	v_mov_b32_e32 v51, v0
	v_mov_b32_e32 v52, v0
	v_mov_b32_e32 v53, v0
	v_mov_b32_e32 v54, v0
	v_mov_b32_e32 v55, v0
	v_mov_b32_e32 v8, v0
	v_mov_b32_e32 v9, v0
	v_mov_b32_e32 v10, v0
	v_mov_b32_e32 v11, v0
	v_mov_b32_e32 v12, v0
	v_mov_b32_e32 v13, v0
	v_mov_b32_e32 v14, v0
	v_mov_b32_e32 v15, v0
	v_mov_b32_e32 v24, v0
	v_mov_b32_e32 v25, v0
	v_mov_b32_e32 v26, v0
	v_mov_b32_e32 v27, v0
	v_mov_b32_e32 v28, v0
	v_mov_b32_e32 v29, v0
	v_mov_b32_e32 v30, v0
	v_mov_b32_e32 v31, v0
	v_mov_b32_e32 v40, v0
	v_mov_b32_e32 v41, v0
	v_mov_b32_e32 v42, v0
	v_mov_b32_e32 v43, v0
	v_mov_b32_e32 v44, v0
	v_mov_b32_e32 v45, v0
	v_mov_b32_e32 v46, v0
	v_mov_b32_e32 v47, v0
	v_mov_b32_e32 v56, v0
	v_mov_b32_e32 v57, v0
	v_mov_b32_e32 v58, v0
	v_mov_b32_e32 v59, v0
	v_mov_b32_e32 v60, v0
	v_mov_b32_e32 v61, v0
	v_mov_b32_e32 v62, v0
	v_mov_b32_e32 v63, v0
	v_mov_b32_e32 v64, v0
	v_mov_b32_e32 v65, v0
	v_mov_b32_e32 v66, v0
	v_mov_b32_e32 v67, v0
	v_mov_b32_e32 v68, v0
	v_mov_b32_e32 v69, v0
	v_mov_b32_e32 v70, v0
	v_mov_b32_e32 v71, v0
	v_mov_b32_e32 v80, v0
	v_mov_b32_e32 v81, v0
	v_mov_b32_e32 v82, v0
	v_mov_b32_e32 v83, v0
	v_mov_b32_e32 v84, v0
	v_mov_b32_e32 v85, v0
	v_mov_b32_e32 v86, v0
	v_mov_b32_e32 v87, v0
	v_mov_b32_e32 v96, v0
	v_mov_b32_e32 v97, v0
	v_mov_b32_e32 v98, v0
	v_mov_b32_e32 v99, v0
	v_mov_b32_e32 v100, v0
	v_mov_b32_e32 v101, v0
	v_mov_b32_e32 v102, v0
	v_mov_b32_e32 v103, v0
	v_mov_b32_e32 v112, v0
	v_mov_b32_e32 v113, v0
	v_mov_b32_e32 v114, v0
	v_mov_b32_e32 v115, v0
	v_mov_b32_e32 v116, v0
	v_mov_b32_e32 v117, v0
	v_mov_b32_e32 v118, v0
	v_mov_b32_e32 v119, v0
	v_mov_b32_e32 v72, v0
	v_mov_b32_e32 v73, v0
	v_mov_b32_e32 v74, v0
	v_mov_b32_e32 v75, v0
	v_mov_b32_e32 v76, v0
	v_mov_b32_e32 v77, v0
	v_mov_b32_e32 v78, v0
	v_mov_b32_e32 v79, v0
	v_mov_b32_e32 v88, v0
	v_mov_b32_e32 v89, v0
	v_mov_b32_e32 v90, v0
	v_mov_b32_e32 v91, v0
	v_mov_b32_e32 v92, v0
	v_mov_b32_e32 v93, v0
	v_mov_b32_e32 v94, v0
	v_mov_b32_e32 v95, v0
	v_mov_b32_e32 v104, v0
	v_mov_b32_e32 v105, v0
	v_mov_b32_e32 v106, v0
	v_mov_b32_e32 v107, v0
	v_mov_b32_e32 v108, v0
	v_mov_b32_e32 v109, v0
	v_mov_b32_e32 v110, v0
	v_mov_b32_e32 v111, v0
	v_mov_b32_e32 v120, v0
	v_mov_b32_e32 v121, v0
	v_mov_b32_e32 v122, v0
	v_mov_b32_e32 v123, v0
	v_mov_b32_e32 v124, v0
	v_mov_b32_e32 v125, v0
	v_mov_b32_e32 v126, v0
	v_mov_b32_e32 v127, v0
.LBB0_888:
	ds_read_b128 v[164:167], v155
	ds_read_b128 v[168:171], v155 offset:1024
	ds_read_b128 v[172:175], v155 offset:2048
	ds_read_b128 v[176:179], v155 offset:3072
	ds_read_b128 v[180:183], v156
	ds_read_b128 v[188:191], v156 offset:1024
	ds_read_b128 v[192:195], v156 offset:2048
	ds_read_b128 v[196:199], v156 offset:3072
	s_add_u32 s53, s34, 0xfffc0080
	s_addc_u32 s54, s35, -1
	s_cmp_eq_u32 s23, 12
	s_cselect_b64 vcc, -1, 0
	s_and_b64 s[36:37], vcc, exec
	v_cndmask_b32_e32 v159, v151, v149, vcc
	s_cselect_b32 s37, s21, s54
	s_cselect_b32 s36, s25, s53
	v_cndmask_b32_e32 v158, v150, v148, vcc
	v_lshl_add_u64 v[232:233], s[34:35], 0, v[138:139]
	s_add_i32 m0, s29, 0xc000
	ds_read_b128 v[200:203], v157
	ds_read_b128 v[204:207], v157 offset:1024
	ds_read_b128 v[208:211], v157 offset:2048
	ds_read_b128 v[212:215], v157 offset:3072
	ds_read_b128 v[216:219], v157 offset:4096
	ds_read_b128 v[220:223], v157 offset:5120
	ds_read_b128 v[224:227], v157 offset:6144
	ds_read_b128 v[228:231], v157 offset:7168
	global_load_lds_dwordx4 v[232:233], off
	v_lshl_add_u64 v[232:233], s[34:35], 0, v[140:141]
	s_add_i32 m0, s29, 0xe000
	s_nop 0
	global_load_lds_dwordx4 v[232:233], off
	s_waitcnt vmcnt(8)
	s_waitcnt lgkmcnt(0)
	s_barrier
	s_setprio 1
	s_waitcnt lgkmcnt(0)
	v_mfma_f32_16x16x32_bf16 v[124:127], v[164:167], v[200:203], v[124:127]
	v_mfma_f32_16x16x32_bf16 v[120:123], v[172:175], v[200:203], v[120:123]
	v_mfma_f32_16x16x32_bf16 v[108:111], v[164:167], v[208:211], v[108:111]
	v_mfma_f32_16x16x32_bf16 v[104:107], v[172:175], v[208:211], v[104:107]
	v_mfma_f32_16x16x32_bf16 v[92:95], v[164:167], v[216:219], v[92:95]
	v_mfma_f32_16x16x32_bf16 v[88:91], v[172:175], v[216:219], v[88:91]
	v_mfma_f32_16x16x32_bf16 v[76:79], v[164:167], v[224:227], v[76:79]
	v_mfma_f32_16x16x32_bf16 v[72:75], v[172:175], v[224:227], v[72:75]
	v_mfma_f32_16x16x32_bf16 v[124:127], v[168:171], v[204:207], v[124:127]
	v_mfma_f32_16x16x32_bf16 v[120:123], v[176:179], v[204:207], v[120:123]
	v_mfma_f32_16x16x32_bf16 v[108:111], v[168:171], v[212:215], v[108:111]
	v_mfma_f32_16x16x32_bf16 v[104:107], v[176:179], v[212:215], v[104:107]
	v_mfma_f32_16x16x32_bf16 v[92:95], v[168:171], v[220:223], v[92:95]
	v_mfma_f32_16x16x32_bf16 v[88:91], v[176:179], v[220:223], v[88:91]
	v_mfma_f32_16x16x32_bf16 v[76:79], v[168:171], v[228:231], v[76:79]
	v_mfma_f32_16x16x32_bf16 v[72:75], v[176:179], v[228:231], v[72:75]
	s_setprio 0
	s_setprio 1
	v_mfma_f32_16x16x32_bf16 v[116:119], v[180:183], v[200:203], v[116:119]
	v_mfma_f32_16x16x32_bf16 v[112:115], v[192:195], v[200:203], v[112:115]
	v_mfma_f32_16x16x32_bf16 v[100:103], v[180:183], v[208:211], v[100:103]
	v_mfma_f32_16x16x32_bf16 v[96:99], v[192:195], v[208:211], v[96:99]
	v_mfma_f32_16x16x32_bf16 v[84:87], v[180:183], v[216:219], v[84:87]
	v_mfma_f32_16x16x32_bf16 v[80:83], v[192:195], v[216:219], v[80:83]
	v_mfma_f32_16x16x32_bf16 v[68:71], v[180:183], v[224:227], v[68:71]
	v_mfma_f32_16x16x32_bf16 v[64:67], v[192:195], v[224:227], v[64:67]
	v_mfma_f32_16x16x32_bf16 v[116:119], v[188:191], v[204:207], v[116:119]
	v_mfma_f32_16x16x32_bf16 v[112:115], v[196:199], v[204:207], v[112:115]
	v_mfma_f32_16x16x32_bf16 v[100:103], v[188:191], v[212:215], v[100:103]
	v_mfma_f32_16x16x32_bf16 v[96:99], v[196:199], v[212:215], v[96:99]
	v_mfma_f32_16x16x32_bf16 v[84:87], v[188:191], v[220:223], v[84:87]
	v_mfma_f32_16x16x32_bf16 v[80:83], v[196:199], v[220:223], v[80:83]
	v_mfma_f32_16x16x32_bf16 v[68:71], v[188:191], v[228:231], v[68:71]
	v_mfma_f32_16x16x32_bf16 v[64:67], v[196:199], v[228:231], v[64:67]
	s_setprio 0
	s_barrier
	s_add_i32 s53, s50, s33
	v_lshl_add_u64 v[232:233], v[158:159], 0, v[134:135]
	s_mov_b32 m0, s53
	ds_read_b128 v[200:203], v157 offset:16384
	ds_read_b128 v[204:207], v157 offset:17408
	ds_read_b128 v[208:211], v157 offset:18432
	ds_read_b128 v[212:215], v157 offset:19456
	ds_read_b128 v[216:219], v157 offset:20480
	ds_read_b128 v[220:223], v157 offset:21504
	ds_read_b128 v[224:227], v157 offset:22528
	ds_read_b128 v[228:231], v157 offset:23552
	global_load_lds_dwordx4 v[232:233], off
	v_lshl_add_u64 v[236:237], v[158:159], 0, v[130:131]
	s_add_i32 m0, s53, 0x2000
	v_lshl_add_u64 v[238:239], v[158:159], 0, s[8:9]
	s_add_i32 s53, s51, s33
	global_load_lds_dwordx4 v[236:237], off
	v_lshl_add_u64 v[240:241], v[238:239], 0, v[134:135]
	s_mov_b32 m0, s53
	v_lshl_add_u64 v[238:239], v[238:239], 0, v[130:131]
	global_load_lds_dwordx4 v[240:241], off
	s_add_i32 m0, s53, 0x2000
	v_lshl_add_u64 v[240:241], s[36:37], 0, v[132:133]
	global_load_lds_dwordx4 v[238:239], off
	v_lshl_add_u64 v[238:239], s[36:37], 0, v[136:137]
	s_mov_b32 m0, s29
	s_nop 0
	global_load_lds_dwordx4 v[238:239], off
	s_mov_b32 m0, s31
	s_nop 0
	global_load_lds_dwordx4 v[240:241], off
	s_waitcnt vmcnt(8)
	s_waitcnt lgkmcnt(0)
	s_barrier
	s_setprio 1
	s_waitcnt lgkmcnt(0)
	s_cmp_eq_u32 s42, 2
	s_cbranch_scc0 .Lm1_kfull_a
	s_cmp_eq_u32 s48, 0x100
	s_cbranch_scc1 .Lm1_kskip_a
.Lm1_kfull_a:
	v_mfma_f32_16x16x32_bf16 v[60:63], v[164:167], v[200:203], v[60:63]
	v_mfma_f32_16x16x32_bf16 v[56:59], v[172:175], v[200:203], v[56:59]
	v_mfma_f32_16x16x32_bf16 v[44:47], v[164:167], v[208:211], v[44:47]
	v_mfma_f32_16x16x32_bf16 v[40:43], v[172:175], v[208:211], v[40:43]
	v_mfma_f32_16x16x32_bf16 v[28:31], v[164:167], v[216:219], v[28:31]
	v_mfma_f32_16x16x32_bf16 v[24:27], v[172:175], v[216:219], v[24:27]
	v_mfma_f32_16x16x32_bf16 v[12:15], v[164:167], v[224:227], v[12:15]
	v_mfma_f32_16x16x32_bf16 v[8:11], v[172:175], v[224:227], v[8:11]
	v_mfma_f32_16x16x32_bf16 v[60:63], v[168:171], v[204:207], v[60:63]
	v_mfma_f32_16x16x32_bf16 v[56:59], v[176:179], v[204:207], v[56:59]
	v_mfma_f32_16x16x32_bf16 v[44:47], v[168:171], v[212:215], v[44:47]
	v_mfma_f32_16x16x32_bf16 v[40:43], v[176:179], v[212:215], v[40:43]
	v_mfma_f32_16x16x32_bf16 v[28:31], v[168:171], v[220:223], v[28:31]
	v_mfma_f32_16x16x32_bf16 v[24:27], v[176:179], v[220:223], v[24:27]
	v_mfma_f32_16x16x32_bf16 v[12:15], v[168:171], v[228:231], v[12:15]
	v_mfma_f32_16x16x32_bf16 v[8:11], v[176:179], v[228:231], v[8:11]
	s_setprio 0
	s_setprio 1
	v_mfma_f32_16x16x32_bf16 v[52:55], v[180:183], v[200:203], v[52:55]
	v_mfma_f32_16x16x32_bf16 v[48:51], v[192:195], v[200:203], v[48:51]
	v_mfma_f32_16x16x32_bf16 v[36:39], v[180:183], v[208:211], v[36:39]
	v_mfma_f32_16x16x32_bf16 v[32:35], v[192:195], v[208:211], v[32:35]
	v_mfma_f32_16x16x32_bf16 v[20:23], v[180:183], v[216:219], v[20:23]
	v_mfma_f32_16x16x32_bf16 v[16:19], v[192:195], v[216:219], v[16:19]
	v_mfma_f32_16x16x32_bf16 v[4:7], v[180:183], v[224:227], v[4:7]
	v_mfma_f32_16x16x32_bf16 v[0:3], v[192:195], v[224:227], v[0:3]
	v_mfma_f32_16x16x32_bf16 v[52:55], v[188:191], v[204:207], v[52:55]
	v_mfma_f32_16x16x32_bf16 v[48:51], v[196:199], v[204:207], v[48:51]
	v_mfma_f32_16x16x32_bf16 v[36:39], v[188:191], v[212:215], v[36:39]
	v_mfma_f32_16x16x32_bf16 v[32:35], v[196:199], v[212:215], v[32:35]
	v_mfma_f32_16x16x32_bf16 v[20:23], v[188:191], v[220:223], v[20:23]
	v_mfma_f32_16x16x32_bf16 v[16:19], v[196:199], v[220:223], v[16:19]
	v_mfma_f32_16x16x32_bf16 v[4:7], v[188:191], v[228:231], v[4:7]
	v_mfma_f32_16x16x32_bf16 v[0:3], v[196:199], v[228:231], v[0:3]
.Lm1_kskip_a:
	s_setprio 0
	s_barrier
	s_add_i32 s53, 0, 0x18000
	s_add_i32 s54, 0, 0x1c000
	v_add_u32_e32 v176, s53, v154
	v_add_u32_e32 v196, s54, v154
	ds_read_b128 v[164:167], v176
	ds_read_b128 v[168:171], v176 offset:1024
	ds_read_b128 v[172:175], v176 offset:2048
	ds_read_b128 v[176:179], v176 offset:3072
	ds_read_b128 v[180:183], v196
	ds_read_b128 v[188:191], v196 offset:1024
	ds_read_b128 v[192:195], v196 offset:2048
	ds_read_b128 v[196:199], v196 offset:3072
	s_add_u32 s36, s36, 0x40000
	s_addc_u32 s37, s37, 0
	s_mov_b32 m0, s40
	v_lshl_add_u64 v[242:243], s[36:37], 0, v[136:137]
	ds_read_b128 v[200:203], v157 offset:32768
	ds_read_b128 v[204:207], v157 offset:33792
	ds_read_b128 v[208:211], v157 offset:34816
	ds_read_b128 v[212:215], v157 offset:35840
	ds_read_b128 v[216:219], v157 offset:36864
	ds_read_b128 v[220:223], v157 offset:37888
	ds_read_b128 v[224:227], v157 offset:38912
	ds_read_b128 v[228:231], v157 offset:39936
	global_load_lds_dwordx4 v[242:243], off
	v_lshl_add_u64 v[242:243], s[36:37], 0, v[132:133]
	s_mov_b32 m0, s41
	s_nop 0
	global_load_lds_dwordx4 v[242:243], off
	s_waitcnt vmcnt(8)
	s_waitcnt lgkmcnt(0)
	s_barrier
	s_setprio 1
	s_waitcnt lgkmcnt(0)
	v_mfma_f32_16x16x32_bf16 v[124:127], v[164:167], v[200:203], v[124:127]
	v_mfma_f32_16x16x32_bf16 v[120:123], v[172:175], v[200:203], v[120:123]
	v_mfma_f32_16x16x32_bf16 v[108:111], v[164:167], v[208:211], v[108:111]
	v_mfma_f32_16x16x32_bf16 v[104:107], v[172:175], v[208:211], v[104:107]
	v_mfma_f32_16x16x32_bf16 v[92:95], v[164:167], v[216:219], v[92:95]
	v_mfma_f32_16x16x32_bf16 v[88:91], v[172:175], v[216:219], v[88:91]
	v_mfma_f32_16x16x32_bf16 v[76:79], v[164:167], v[224:227], v[76:79]
	v_mfma_f32_16x16x32_bf16 v[72:75], v[172:175], v[224:227], v[72:75]
	v_mfma_f32_16x16x32_bf16 v[124:127], v[168:171], v[204:207], v[124:127]
	v_mfma_f32_16x16x32_bf16 v[120:123], v[176:179], v[204:207], v[120:123]
	v_mfma_f32_16x16x32_bf16 v[108:111], v[168:171], v[212:215], v[108:111]
	v_mfma_f32_16x16x32_bf16 v[104:107], v[176:179], v[212:215], v[104:107]
	v_mfma_f32_16x16x32_bf16 v[92:95], v[168:171], v[220:223], v[92:95]
	v_mfma_f32_16x16x32_bf16 v[88:91], v[176:179], v[220:223], v[88:91]
	v_mfma_f32_16x16x32_bf16 v[76:79], v[168:171], v[228:231], v[76:79]
	v_mfma_f32_16x16x32_bf16 v[72:75], v[176:179], v[228:231], v[72:75]
	s_setprio 0
	s_setprio 1
	v_mfma_f32_16x16x32_bf16 v[116:119], v[180:183], v[200:203], v[116:119]
	v_mfma_f32_16x16x32_bf16 v[112:115], v[192:195], v[200:203], v[112:115]
	v_mfma_f32_16x16x32_bf16 v[100:103], v[180:183], v[208:211], v[100:103]
	v_mfma_f32_16x16x32_bf16 v[96:99], v[192:195], v[208:211], v[96:99]
	v_mfma_f32_16x16x32_bf16 v[84:87], v[180:183], v[216:219], v[84:87]
	v_mfma_f32_16x16x32_bf16 v[80:83], v[192:195], v[216:219], v[80:83]
	v_mfma_f32_16x16x32_bf16 v[68:71], v[180:183], v[224:227], v[68:71]
	v_mfma_f32_16x16x32_bf16 v[64:67], v[192:195], v[224:227], v[64:67]
	v_mfma_f32_16x16x32_bf16 v[116:119], v[188:191], v[204:207], v[116:119]
	v_mfma_f32_16x16x32_bf16 v[112:115], v[196:199], v[204:207], v[112:115]
	v_mfma_f32_16x16x32_bf16 v[100:103], v[188:191], v[212:215], v[100:103]
	v_mfma_f32_16x16x32_bf16 v[96:99], v[196:199], v[212:215], v[96:99]
	v_mfma_f32_16x16x32_bf16 v[84:87], v[188:191], v[220:223], v[84:87]
	v_mfma_f32_16x16x32_bf16 v[80:83], v[196:199], v[220:223], v[80:83]
	v_mfma_f32_16x16x32_bf16 v[68:71], v[188:191], v[228:231], v[68:71]
	v_mfma_f32_16x16x32_bf16 v[64:67], v[196:199], v[228:231], v[64:67]
	s_setprio 0
	s_barrier
	s_add_i32 s36, s53, s33
	v_lshl_add_u64 v[232:233], v[232:233], 0, s[12:13]
	s_mov_b32 m0, s36
	ds_read_b128 v[200:203], v157 offset:49152
	ds_read_b128 v[204:207], v157 offset:50176
	ds_read_b128 v[208:211], v157 offset:51200
	ds_read_b128 v[212:215], v157 offset:52224
	ds_read_b128 v[216:219], v157 offset:53248
	ds_read_b128 v[220:223], v157 offset:54272
	ds_read_b128 v[224:227], v157 offset:55296
	ds_read_b128 v[228:231], v157 offset:56320
	global_load_lds_dwordx4 v[232:233], off
	v_lshl_add_u64 v[232:233], v[236:237], 0, s[12:13]
	s_add_i32 m0, s36, 0x2000
	v_lshl_add_u64 v[158:159], v[158:159], 0, s[14:15]
	s_add_i32 s36, s54, s33
	global_load_lds_dwordx4 v[232:233], off
	v_lshl_add_u64 v[232:233], v[158:159], 0, v[134:135]
	s_mov_b32 m0, s36
	v_lshl_add_u64 v[158:159], v[158:159], 0, v[130:131]
	global_load_lds_dwordx4 v[232:233], off
	s_add_i32 m0, s36, 0x2000
	s_nop 0
	global_load_lds_dwordx4 v[158:159], off
	v_lshl_add_u64 v[158:159], v[238:239], 0, s[12:13]
	s_mov_b32 m0, s43
	s_nop 0
	global_load_lds_dwordx4 v[158:159], off
	v_lshl_add_u64 v[158:159], v[240:241], 0, s[12:13]
	s_mov_b32 m0, s44
	s_nop 0
	global_load_lds_dwordx4 v[158:159], off
	s_waitcnt vmcnt(8)
	s_waitcnt lgkmcnt(0)
	s_barrier
	s_setprio 1
	s_waitcnt lgkmcnt(0)
	s_cmp_eq_u32 s42, 2
	s_cbranch_scc0 .Lm1_kfull_b
	s_cmp_eq_u32 s48, 0x100
	s_cbranch_scc1 .Lm1_kskip_b

.LBB0_891:
	v_mov_b32_e32 v148, v152
	v_mov_b32_e32 v149, v153
	s_lshl_b32 s21, s30, 8
	s_add_i32 s21, s21, s45
	s_cmp_eq_u32 s42, 2
	s_cbranch_scc0 .Lm1_rb_skip
	s_cmp_eq_u32 s48, 0x100
	s_cbranch_scc0 .Lm1_rb_skip
	s_and_b32 s98, s2, 1
	s_lshl_b32 s98, s98, 7
	s_add_i32 s21, s21, s98
.Lm1_rb_skip:
	v_add_u32_e32 v148, s21, v148
	s_lshl_b32 s21, s28, 8
	s_or_b32 s21, s21, s46
	v_lshl_add_u32 v150, v149, 3, s21
	v_ashrrev_i32_e32 v149, 31, v148
	v_ashrrev_i32_e32 v151, 31, v150
	v_lshlrev_b64 v[158:159], 12, v[148:149]
	v_lshlrev_b64 v[168:169], 11, v[148:149]
	v_lshl_add_u64 v[158:159], v[162:163], 0, v[158:159]
	v_lshlrev_b64 v[150:151], 1, v[150:151]
	v_lshl_add_u64 v[168:169], v[186:187], 0, v[168:169]
	v_lshl_add_u64 v[158:159], v[158:159], 0, v[150:151]
	v_lshl_add_u64 v[200:201], v[168:169], 0, v[150:151]
	global_load_dwordx4 v[164:167], v[158:159], off offset:2048
	global_load_dwordx4 v[168:171], v[200:201], off
	global_load_dwordx4 v[172:175], v[158:159], off offset:2304
	global_load_dwordx4 v[176:179], v[200:201], off offset:256
	v_add_u32_e32 v158, 16, v148
	v_ashrrev_i32_e32 v159, 31, v158
	v_lshlrev_b64 v[180:181], 12, v[158:159]
	v_lshl_add_u64 v[180:181], v[162:163], 0, v[180:181]
	v_lshl_add_u64 v[192:193], v[180:181], 0, v[150:151]
	v_lshlrev_b64 v[158:159], 11, v[158:159]
	global_load_dwordx4 v[180:183], v[192:193], off offset:2048
	v_lshl_add_u64 v[158:159], v[186:187], 0, v[158:159]
	v_lshl_add_u64 v[158:159], v[158:159], 0, v[150:151]
	global_load_dwordx4 v[188:191], v[158:159], off
	s_nop 0
	global_load_dwordx4 v[192:195], v[192:193], off offset:2304
	s_nop 0
	global_load_dwordx4 v[196:199], v[158:159], off offset:256
	s_andn2_b64 vcc, exec, s[6:7]
	s_mov_b64 s[6:7], -1
	s_waitcnt vmcnt(0)
	v_lshlrev_b32_e32 v206, 16, v168
	v_lshlrev_b32_e32 v202, 16, v164
	v_and_b32_e32 v203, 0xffff0000, v164
	v_lshlrev_b32_e32 v164, 16, v165
	v_and_b32_e32 v165, 0xffff0000, v165
	v_lshlrev_b32_e32 v204, 16, v166
	v_and_b32_e32 v205, 0xffff0000, v166
	v_lshlrev_b32_e32 v166, 16, v167
	v_and_b32_e32 v167, 0xffff0000, v167
	v_and_b32_e32 v207, 0xffff0000, v168
	v_lshlrev_b32_e32 v168, 16, v169
	v_and_b32_e32 v169, 0xffff0000, v169
	v_lshlrev_b32_e32 v208, 16, v170
	v_and_b32_e32 v209, 0xffff0000, v170
	v_lshlrev_b32_e32 v170, 16, v171
	v_and_b32_e32 v171, 0xffff0000, v171
	v_lshlrev_b32_e32 v210, 16, v172
	v_and_b32_e32 v211, 0xffff0000, v172
	v_lshlrev_b32_e32 v172, 16, v173
	v_and_b32_e32 v173, 0xffff0000, v173
	v_lshlrev_b32_e32 v212, 16, v174
	v_and_b32_e32 v213, 0xffff0000, v174
	v_lshlrev_b32_e32 v174, 16, v175
	v_and_b32_e32 v175, 0xffff0000, v175
	v_lshlrev_b32_e32 v214, 16, v176
	v_and_b32_e32 v215, 0xffff0000, v176
	v_lshlrev_b32_e32 v176, 16, v177
	v_and_b32_e32 v177, 0xffff0000, v177
	v_lshlrev_b32_e32 v216, 16, v178
	v_and_b32_e32 v217, 0xffff0000, v178
	v_lshlrev_b32_e32 v178, 16, v179
	v_and_b32_e32 v179, 0xffff0000, v179
	v_pk_fma_f32 v[126:127], v[126:127], v[164:165], v[168:169]
	v_pk_fma_f32 v[124:125], v[124:125], v[202:203], v[206:207]
	v_pk_fma_f32 v[122:123], v[122:123], v[166:167], v[170:171]
	v_pk_fma_f32 v[120:121], v[120:121], v[204:205], v[208:209]
	v_pk_fma_f32 v[118:119], v[118:119], v[172:173], v[176:177]
	v_pk_fma_f32 v[116:117], v[116:117], v[210:211], v[214:215]
	v_pk_fma_f32 v[164:165], v[114:115], v[174:175], v[178:179]
	v_pk_fma_f32 v[166:167], v[112:113], v[212:213], v[216:217]
	v_cvt_pk_bf16_f32 v112, v124, v125
	v_cvt_pk_bf16_f32 v113, v126, v127
	v_cvt_pk_bf16_f32 v114, v120, v121
	v_cvt_pk_bf16_f32 v115, v122, v123
	v_lshlrev_b32_e32 v168, 16, v180
	v_and_b32_e32 v169, 0xffff0000, v180
	v_cvt_pk_bf16_f32 v116, v116, v117
	v_cvt_pk_bf16_f32 v117, v118, v119
	v_cvt_pk_bf16_f32 v118, v166, v167
	v_cvt_pk_bf16_f32 v119, v164, v165
	global_store_dwordx4 v[200:201], v[112:115], off
	global_store_dwordx4 v[200:201], v[116:119], off offset:256
	v_lshlrev_b32_e32 v170, 16, v181
	v_lshlrev_b32_e32 v112, 16, v188
	v_and_b32_e32 v113, 0xffff0000, v188
	v_and_b32_e32 v171, 0xffff0000, v181
	v_lshlrev_b32_e32 v172, 16, v182
	v_and_b32_e32 v173, 0xffff0000, v182
	v_lshlrev_b32_e32 v174, 16, v183
	v_and_b32_e32 v175, 0xffff0000, v183
	v_lshlrev_b32_e32 v114, 16, v189
	v_and_b32_e32 v115, 0xffff0000, v189
	v_lshlrev_b32_e32 v116, 16, v190
	v_and_b32_e32 v117, 0xffff0000, v190
	v_lshlrev_b32_e32 v118, 16, v191
	v_and_b32_e32 v119, 0xffff0000, v191
	v_pk_fma_f32 v[108:109], v[108:109], v[168:169], v[112:113]
	v_pk_fma_f32 v[110:111], v[110:111], v[170:171], v[114:115]
	v_pk_fma_f32 v[112:113], v[106:107], v[174:175], v[118:119]
	v_pk_fma_f32 v[106:107], v[104:105], v[172:173], v[116:117]
	v_cvt_pk_bf16_f32 v104, v108, v109
	v_add_u32_e32 v108, 32, v148
	v_cvt_pk_bf16_f32 v105, v110, v111
	v_cvt_pk_bf16_f32 v106, v106, v107
	v_cvt_pk_bf16_f32 v107, v112, v113
	v_ashrrev_i32_e32 v109, 31, v108
	global_store_dwordx4 v[158:159], v[104:107], off
	v_lshlrev_b32_e32 v112, 16, v192
	v_and_b32_e32 v113, 0xffff0000, v192
	v_lshlrev_b64 v[104:105], 11, v[108:109]
	v_lshlrev_b64 v[108:109], 12, v[108:109]
	v_lshl_add_u64 v[104:105], v[186:187], 0, v[104:105]
	v_lshl_add_u64 v[108:109], v[162:163], 0, v[108:109]
	v_lshlrev_b32_e32 v114, 16, v193
	v_and_b32_e32 v115, 0xffff0000, v193
	v_lshlrev_b32_e32 v116, 16, v194
	v_lshl_add_u64 v[164:165], v[104:105], 0, v[150:151]
	v_and_b32_e32 v117, 0xffff0000, v194
	v_lshlrev_b32_e32 v118, 16, v195
	v_and_b32_e32 v119, 0xffff0000, v195
	v_lshl_add_u64 v[120:121], v[108:109], 0, v[150:151]
	v_lshlrev_b32_e32 v122, 16, v196
	v_and_b32_e32 v123, 0xffff0000, v196
	v_lshlrev_b32_e32 v124, 16, v197
	v_and_b32_e32 v125, 0xffff0000, v197
	v_lshlrev_b32_e32 v126, 16, v198
	v_and_b32_e32 v127, 0xffff0000, v198
	v_lshlrev_b32_e32 v166, 16, v199
	v_and_b32_e32 v167, 0xffff0000, v199
	global_load_dwordx4 v[104:107], v[164:165], off
	global_load_dwordx4 v[108:111], v[120:121], off offset:2048
	v_pk_fma_f32 v[102:103], v[102:103], v[114:115], v[124:125]
	v_pk_fma_f32 v[100:101], v[100:101], v[112:113], v[122:123]
	v_pk_fma_f32 v[112:113], v[98:99], v[118:119], v[166:167]
	v_pk_fma_f32 v[98:99], v[96:97], v[116:117], v[126:127]
	v_cvt_pk_bf16_f32 v96, v100, v101
	v_cvt_pk_bf16_f32 v97, v102, v103
	v_cvt_pk_bf16_f32 v98, v98, v99
	v_cvt_pk_bf16_f32 v99, v112, v113
	v_add_u32_e32 v116, 48, v148
	global_store_dwordx4 v[158:159], v[96:99], off offset:256
	v_ashrrev_i32_e32 v117, 31, v116
	global_load_dwordx4 v[96:99], v[120:121], off offset:2304
	global_load_dwordx4 v[100:103], v[164:165], off offset:256
	v_lshlrev_b64 v[112:113], 12, v[116:117]
	v_lshl_add_u64 v[112:113], v[162:163], 0, v[112:113]
	v_lshl_add_u64 v[120:121], v[112:113], 0, v[150:151]
	v_lshlrev_b64 v[116:117], 11, v[116:117]
	global_load_dwordx4 v[112:115], v[120:121], off offset:2048
	v_lshl_add_u64 v[116:117], v[186:187], 0, v[116:117]
	v_lshl_add_u64 v[158:159], v[116:117], 0, v[150:151]
	global_load_dwordx4 v[116:119], v[158:159], off
	s_nop 0
	global_load_dwordx4 v[120:123], v[120:121], off offset:2304
	s_nop 0
	global_load_dwordx4 v[124:127], v[158:159], off offset:256
	s_waitcnt vmcnt(8)
	v_lshlrev_b32_e32 v166, 16, v104
	v_and_b32_e32 v167, 0xffff0000, v104
	v_lshlrev_b32_e32 v104, 16, v105
	v_and_b32_e32 v105, 0xffff0000, v105
	v_lshlrev_b32_e32 v168, 16, v106
	v_and_b32_e32 v169, 0xffff0000, v106
	v_lshlrev_b32_e32 v106, 16, v107
	s_waitcnt vmcnt(7)
	v_lshlrev_b32_e32 v170, 16, v108
	v_and_b32_e32 v171, 0xffff0000, v108
	v_lshlrev_b32_e32 v108, 16, v109
	v_and_b32_e32 v109, 0xffff0000, v109
	v_lshlrev_b32_e32 v172, 16, v110
	v_and_b32_e32 v173, 0xffff0000, v110
	v_lshlrev_b32_e32 v110, 16, v111
	v_and_b32_e32 v111, 0xffff0000, v111
	v_and_b32_e32 v107, 0xffff0000, v107
	v_pk_fma_f32 v[94:95], v[94:95], v[108:109], v[104:105]
	v_pk_fma_f32 v[92:93], v[92:93], v[170:171], v[166:167]
	v_pk_fma_f32 v[104:105], v[90:91], v[110:111], v[106:107]
	v_pk_fma_f32 v[90:91], v[88:89], v[172:173], v[168:169]
	v_cvt_pk_bf16_f32 v88, v92, v93
	v_cvt_pk_bf16_f32 v89, v94, v95
	v_cvt_pk_bf16_f32 v90, v90, v91
	v_cvt_pk_bf16_f32 v91, v104, v105
	global_store_dwordx4 v[164:165], v[88:91], off
	s_waitcnt vmcnt(6)
	v_lshlrev_b32_e32 v92, 16, v98
	v_and_b32_e32 v93, 0xffff0000, v98
	v_lshlrev_b32_e32 v88, 16, v96
	v_and_b32_e32 v89, 0xffff0000, v96
	v_lshlrev_b32_e32 v90, 16, v97
	v_and_b32_e32 v91, 0xffff0000, v97
	v_lshlrev_b32_e32 v94, 16, v99
	v_and_b32_e32 v95, 0xffff0000, v99
	s_waitcnt vmcnt(5)
	v_lshlrev_b32_e32 v96, 16, v100
	v_and_b32_e32 v97, 0xffff0000, v100
	v_lshlrev_b32_e32 v98, 16, v101
	v_and_b32_e32 v99, 0xffff0000, v101
	v_lshlrev_b32_e32 v100, 16, v102
	v_and_b32_e32 v101, 0xffff0000, v102
	v_lshlrev_b32_e32 v102, 16, v103
	v_and_b32_e32 v103, 0xffff0000, v103
	v_pk_fma_f32 v[86:87], v[86:87], v[90:91], v[98:99]
	v_pk_fma_f32 v[84:85], v[84:85], v[88:89], v[96:97]
	v_pk_fma_f32 v[88:89], v[82:83], v[94:95], v[102:103]
	v_pk_fma_f32 v[82:83], v[80:81], v[92:93], v[100:101]
	v_cvt_pk_bf16_f32 v80, v84, v85
	v_cvt_pk_bf16_f32 v81, v86, v87
	v_cvt_pk_bf16_f32 v82, v82, v83
	v_cvt_pk_bf16_f32 v83, v88, v89
	global_store_dwordx4 v[164:165], v[80:83], off offset:256
	s_waitcnt vmcnt(4)
	v_lshlrev_b32_e32 v88, 16, v116
	v_and_b32_e32 v89, 0xffff0000, v116
	v_lshlrev_b32_e32 v80, 16, v112
	v_and_b32_e32 v81, 0xffff0000, v112
	v_lshlrev_b32_e32 v82, 16, v113
	v_and_b32_e32 v83, 0xffff0000, v113
	v_lshlrev_b32_e32 v84, 16, v114
	v_and_b32_e32 v85, 0xffff0000, v114
	v_lshlrev_b32_e32 v86, 16, v115
	v_and_b32_e32 v87, 0xffff0000, v115
	v_lshlrev_b32_e32 v90, 16, v117
	v_and_b32_e32 v91, 0xffff0000, v117
	v_lshlrev_b32_e32 v92, 16, v118
	v_and_b32_e32 v93, 0xffff0000, v118
	v_lshlrev_b32_e32 v94, 16, v119
	v_and_b32_e32 v95, 0xffff0000, v119
	v_pk_fma_f32 v[76:77], v[76:77], v[80:81], v[88:89]
	v_pk_fma_f32 v[78:79], v[78:79], v[82:83], v[90:91]
	v_pk_fma_f32 v[80:81], v[74:75], v[86:87], v[94:95]
	v_pk_fma_f32 v[74:75], v[72:73], v[84:85], v[92:93]
	v_cvt_pk_bf16_f32 v72, v76, v77
	v_add_u32_e32 v76, 0x80, v148
	v_cvt_pk_bf16_f32 v73, v78, v79
	v_cvt_pk_bf16_f32 v74, v74, v75
	v_cvt_pk_bf16_f32 v75, v80, v81
	v_ashrrev_i32_e32 v77, 31, v76
	global_store_dwordx4 v[158:159], v[72:75], off
	s_waitcnt vmcnt(4)
	v_lshlrev_b32_e32 v80, 16, v120
	v_and_b32_e32 v81, 0xffff0000, v120
	v_lshlrev_b64 v[72:73], 12, v[76:77]
	v_lshlrev_b64 v[76:77], 11, v[76:77]
	v_lshl_add_u64 v[72:73], v[162:163], 0, v[72:73]
	v_lshl_add_u64 v[76:77], v[186:187], 0, v[76:77]
	v_lshlrev_b32_e32 v82, 16, v121
	v_and_b32_e32 v83, 0xffff0000, v121
	v_lshlrev_b32_e32 v84, 16, v122
	v_lshl_add_u64 v[86:87], v[72:73], 0, v[150:151]
	v_and_b32_e32 v85, 0xffff0000, v122
	v_lshlrev_b32_e32 v88, 16, v123
	v_and_b32_e32 v89, 0xffff0000, v123
	s_waitcnt vmcnt(3)
	v_lshlrev_b32_e32 v90, 16, v124
	v_lshl_add_u64 v[96:97], v[76:77], 0, v[150:151]
	v_and_b32_e32 v91, 0xffff0000, v124
	v_lshlrev_b32_e32 v92, 16, v125
	v_and_b32_e32 v93, 0xffff0000, v125
	v_lshlrev_b32_e32 v94, 16, v126
	v_and_b32_e32 v95, 0xffff0000, v126
	v_lshlrev_b32_e32 v98, 16, v127
	v_and_b32_e32 v99, 0xffff0000, v127
	global_load_dwordx4 v[72:75], v[86:87], off offset:2048
	global_load_dwordx4 v[76:79], v[96:97], off
	v_pk_fma_f32 v[70:71], v[70:71], v[82:83], v[92:93]
	v_pk_fma_f32 v[68:69], v[68:69], v[80:81], v[90:91]
	v_pk_fma_f32 v[80:81], v[66:67], v[88:89], v[98:99]
	v_pk_fma_f32 v[66:67], v[64:65], v[84:85], v[94:95]
	v_cvt_pk_bf16_f32 v64, v68, v69
	v_cvt_pk_bf16_f32 v65, v70, v71
	v_cvt_pk_bf16_f32 v66, v66, v67
	v_cvt_pk_bf16_f32 v67, v80, v81
	v_add_u32_e32 v84, 0x90, v148
	global_store_dwordx4 v[158:159], v[64:67], off offset:256
	s_cmp_eq_u32 s42, 2
	s_cbranch_scc0 .Lm1_epi_full
	s_cmp_eq_u32 s48, 0x100
	s_cbranch_scc1 .Lm1_epi_end
.Lm1_epi_full:
	v_ashrrev_i32_e32 v85, 31, v84
	global_load_dwordx4 v[64:67], v[86:87], off offset:2304
	global_load_dwordx4 v[68:71], v[96:97], off offset:256
	v_lshlrev_b64 v[80:81], 12, v[84:85]
	v_lshl_add_u64 v[80:81], v[162:163], 0, v[80:81]
	v_lshl_add_u64 v[88:89], v[80:81], 0, v[150:151]
	v_lshlrev_b64 v[84:85], 11, v[84:85]
	global_load_dwordx4 v[80:83], v[88:89], off offset:2048
	v_lshl_add_u64 v[84:85], v[186:187], 0, v[84:85]
	v_lshl_add_u64 v[98:99], v[84:85], 0, v[150:151]
	global_load_dwordx4 v[84:87], v[98:99], off
	s_nop 0
	global_load_dwordx4 v[88:91], v[88:89], off offset:2304
	s_nop 0
	global_load_dwordx4 v[92:95], v[98:99], off offset:256
	s_waitcnt vmcnt(8)
	v_lshlrev_b32_e32 v100, 16, v72
	v_and_b32_e32 v101, 0xffff0000, v72
	v_lshlrev_b32_e32 v72, 16, v73
	v_and_b32_e32 v73, 0xffff0000, v73
	v_lshlrev_b32_e32 v102, 16, v74
	v_and_b32_e32 v103, 0xffff0000, v74
	v_lshlrev_b32_e32 v74, 16, v75
	v_and_b32_e32 v75, 0xffff0000, v75
	s_waitcnt vmcnt(7)
	v_lshlrev_b32_e32 v104, 16, v76
	v_and_b32_e32 v105, 0xffff0000, v76
	v_lshlrev_b32_e32 v76, 16, v77
	v_and_b32_e32 v77, 0xffff0000, v77
	v_lshlrev_b32_e32 v106, 16, v78
	v_and_b32_e32 v107, 0xffff0000, v78
	v_lshlrev_b32_e32 v78, 16, v79
	v_and_b32_e32 v79, 0xffff0000, v79
	v_pk_fma_f32 v[62:63], v[62:63], v[72:73], v[76:77]
	v_pk_fma_f32 v[60:61], v[60:61], v[100:101], v[104:105]
	v_pk_fma_f32 v[72:73], v[58:59], v[74:75], v[78:79]
	v_pk_fma_f32 v[58:59], v[56:57], v[102:103], v[106:107]
	v_cvt_pk_bf16_f32 v56, v60, v61
	v_cvt_pk_bf16_f32 v57, v62, v63
	v_cvt_pk_bf16_f32 v58, v58, v59
	v_cvt_pk_bf16_f32 v59, v72, v73
	global_store_dwordx4 v[96:97], v[56:59], off
	s_waitcnt vmcnt(6)
	v_lshlrev_b32_e32 v60, 16, v66
	v_and_b32_e32 v61, 0xffff0000, v66
	v_lshlrev_b32_e32 v56, 16, v64
	v_and_b32_e32 v57, 0xffff0000, v64
	v_lshlrev_b32_e32 v58, 16, v65
	v_and_b32_e32 v59, 0xffff0000, v65
	v_lshlrev_b32_e32 v62, 16, v67
	v_and_b32_e32 v63, 0xffff0000, v67
	s_waitcnt vmcnt(5)
	v_lshlrev_b32_e32 v64, 16, v68
	v_and_b32_e32 v65, 0xffff0000, v68
	v_lshlrev_b32_e32 v66, 16, v69
	v_and_b32_e32 v67, 0xffff0000, v69
	v_lshlrev_b32_e32 v68, 16, v70
	v_and_b32_e32 v69, 0xffff0000, v70
	v_lshlrev_b32_e32 v70, 16, v71
	v_and_b32_e32 v71, 0xffff0000, v71
	v_pk_fma_f32 v[54:55], v[54:55], v[58:59], v[66:67]
	v_pk_fma_f32 v[52:53], v[52:53], v[56:57], v[64:65]
	v_pk_fma_f32 v[56:57], v[50:51], v[62:63], v[70:71]
	v_pk_fma_f32 v[50:51], v[48:49], v[60:61], v[68:69]
	v_cvt_pk_bf16_f32 v48, v52, v53
	v_cvt_pk_bf16_f32 v49, v54, v55
	v_cvt_pk_bf16_f32 v50, v50, v51
	v_cvt_pk_bf16_f32 v51, v56, v57
	global_store_dwordx4 v[96:97], v[48:51], off offset:256
	s_waitcnt vmcnt(4)
	v_lshlrev_b32_e32 v56, 16, v84
	v_and_b32_e32 v57, 0xffff0000, v84
	v_lshlrev_b32_e32 v48, 16, v80
	v_and_b32_e32 v49, 0xffff0000, v80
	v_lshlrev_b32_e32 v50, 16, v81
	v_and_b32_e32 v51, 0xffff0000, v81
	v_lshlrev_b32_e32 v52, 16, v82
	v_and_b32_e32 v53, 0xffff0000, v82
	v_lshlrev_b32_e32 v54, 16, v83
	v_and_b32_e32 v55, 0xffff0000, v83
	v_lshlrev_b32_e32 v58, 16, v85
	v_and_b32_e32 v59, 0xffff0000, v85
	v_lshlrev_b32_e32 v60, 16, v86
	v_and_b32_e32 v61, 0xffff0000, v86
	v_lshlrev_b32_e32 v62, 16, v87
	v_and_b32_e32 v63, 0xffff0000, v87
	v_pk_fma_f32 v[44:45], v[44:45], v[48:49], v[56:57]
	v_pk_fma_f32 v[46:47], v[46:47], v[50:51], v[58:59]
	v_pk_fma_f32 v[48:49], v[42:43], v[54:55], v[62:63]
	v_pk_fma_f32 v[42:43], v[40:41], v[52:53], v[60:61]
	v_cvt_pk_bf16_f32 v40, v44, v45
	v_add_u32_e32 v44, 0xa0, v148
	v_cvt_pk_bf16_f32 v41, v46, v47
	v_cvt_pk_bf16_f32 v42, v42, v43
	v_cvt_pk_bf16_f32 v43, v48, v49
	v_ashrrev_i32_e32 v45, 31, v44
	global_store_dwordx4 v[98:99], v[40:43], off
	s_waitcnt vmcnt(4)
	v_lshlrev_b32_e32 v48, 16, v88
	v_and_b32_e32 v49, 0xffff0000, v88
	v_lshlrev_b64 v[40:41], 12, v[44:45]
	v_lshlrev_b64 v[44:45], 11, v[44:45]
	v_lshl_add_u64 v[40:41], v[162:163], 0, v[40:41]
	v_lshl_add_u64 v[44:45], v[186:187], 0, v[44:45]
	v_lshlrev_b32_e32 v50, 16, v89
	v_and_b32_e32 v51, 0xffff0000, v89
	v_lshlrev_b32_e32 v52, 16, v90
	v_lshl_add_u64 v[54:55], v[40:41], 0, v[150:151]
	v_and_b32_e32 v53, 0xffff0000, v90
	v_lshlrev_b32_e32 v56, 16, v91
	v_and_b32_e32 v57, 0xffff0000, v91
	s_waitcnt vmcnt(3)
	v_lshlrev_b32_e32 v58, 16, v92
	v_lshl_add_u64 v[64:65], v[44:45], 0, v[150:151]
	v_and_b32_e32 v59, 0xffff0000, v92
	v_lshlrev_b32_e32 v60, 16, v93
	v_and_b32_e32 v61, 0xffff0000, v93
	v_lshlrev_b32_e32 v62, 16, v94
	v_and_b32_e32 v63, 0xffff0000, v94
	v_lshlrev_b32_e32 v66, 16, v95
	v_and_b32_e32 v67, 0xffff0000, v95
	global_load_dwordx4 v[40:43], v[54:55], off offset:2048
	global_load_dwordx4 v[44:47], v[64:65], off
	v_pk_fma_f32 v[38:39], v[38:39], v[50:51], v[60:61]
	v_pk_fma_f32 v[36:37], v[36:37], v[48:49], v[58:59]
	v_pk_fma_f32 v[48:49], v[34:35], v[56:57], v[66:67]
	v_pk_fma_f32 v[34:35], v[32:33], v[52:53], v[62:63]
	v_cvt_pk_bf16_f32 v32, v36, v37
	v_cvt_pk_bf16_f32 v33, v38, v39
	v_cvt_pk_bf16_f32 v34, v34, v35
	v_cvt_pk_bf16_f32 v35, v48, v49
	v_add_u32_e32 v52, 0xb0, v148
	global_store_dwordx4 v[98:99], v[32:35], off offset:256
	v_ashrrev_i32_e32 v53, 31, v52
	global_load_dwordx4 v[32:35], v[54:55], off offset:2304
	global_load_dwordx4 v[36:39], v[64:65], off offset:256
	v_lshlrev_b64 v[48:49], 12, v[52:53]
	v_lshl_add_u64 v[48:49], v[162:163], 0, v[48:49]
	v_lshl_add_u64 v[56:57], v[48:49], 0, v[150:151]
	v_lshlrev_b64 v[52:53], 11, v[52:53]
	global_load_dwordx4 v[48:51], v[56:57], off offset:2048
	v_lshl_add_u64 v[52:53], v[186:187], 0, v[52:53]
	v_lshl_add_u64 v[66:67], v[52:53], 0, v[150:151]
	global_load_dwordx4 v[52:55], v[66:67], off
	s_nop 0
	global_load_dwordx4 v[56:59], v[56:57], off offset:2304
	s_nop 0
	global_load_dwordx4 v[60:63], v[66:67], off offset:256
	s_waitcnt vmcnt(8)
	v_lshlrev_b32_e32 v68, 16, v40
	v_and_b32_e32 v69, 0xffff0000, v40
	v_lshlrev_b32_e32 v40, 16, v41
	v_and_b32_e32 v41, 0xffff0000, v41
	v_lshlrev_b32_e32 v70, 16, v42
	v_and_b32_e32 v71, 0xffff0000, v42
	v_lshlrev_b32_e32 v42, 16, v43
	v_and_b32_e32 v43, 0xffff0000, v43
	s_waitcnt vmcnt(7)
	v_lshlrev_b32_e32 v72, 16, v44
	v_and_b32_e32 v73, 0xffff0000, v44
	v_lshlrev_b32_e32 v44, 16, v45
	v_and_b32_e32 v45, 0xffff0000, v45
	v_lshlrev_b32_e32 v74, 16, v46
	v_and_b32_e32 v75, 0xffff0000, v46
	v_lshlrev_b32_e32 v46, 16, v47
	v_and_b32_e32 v47, 0xffff0000, v47
	v_pk_fma_f32 v[30:31], v[30:31], v[40:41], v[44:45]
	v_pk_fma_f32 v[28:29], v[28:29], v[68:69], v[72:73]
	v_pk_fma_f32 v[40:41], v[26:27], v[42:43], v[46:47]
	v_pk_fma_f32 v[26:27], v[24:25], v[70:71], v[74:75]
	v_cvt_pk_bf16_f32 v24, v28, v29
	v_cvt_pk_bf16_f32 v25, v30, v31
	v_cvt_pk_bf16_f32 v26, v26, v27
	v_cvt_pk_bf16_f32 v27, v40, v41
	global_store_dwordx4 v[64:65], v[24:27], off
	s_waitcnt vmcnt(6)
	v_lshlrev_b32_e32 v28, 16, v34
	v_and_b32_e32 v29, 0xffff0000, v34
	v_lshlrev_b32_e32 v24, 16, v32
	v_and_b32_e32 v25, 0xffff0000, v32
	v_lshlrev_b32_e32 v26, 16, v33
	v_and_b32_e32 v27, 0xffff0000, v33
	v_lshlrev_b32_e32 v30, 16, v35
	v_and_b32_e32 v31, 0xffff0000, v35
	s_waitcnt vmcnt(5)
	v_lshlrev_b32_e32 v32, 16, v36
	v_and_b32_e32 v33, 0xffff0000, v36
	v_lshlrev_b32_e32 v34, 16, v37
	v_and_b32_e32 v35, 0xffff0000, v37
	v_lshlrev_b32_e32 v36, 16, v38
	v_and_b32_e32 v37, 0xffff0000, v38
	v_lshlrev_b32_e32 v38, 16, v39
	v_and_b32_e32 v39, 0xffff0000, v39
	v_pk_fma_f32 v[22:23], v[22:23], v[26:27], v[34:35]
	v_pk_fma_f32 v[20:21], v[20:21], v[24:25], v[32:33]
	v_pk_fma_f32 v[24:25], v[18:19], v[30:31], v[38:39]
	v_pk_fma_f32 v[18:19], v[16:17], v[28:29], v[36:37]
	v_cvt_pk_bf16_f32 v16, v20, v21
	v_cvt_pk_bf16_f32 v17, v22, v23
	v_cvt_pk_bf16_f32 v18, v18, v19
	v_cvt_pk_bf16_f32 v19, v24, v25
	global_store_dwordx4 v[64:65], v[16:19], off offset:256
	s_waitcnt vmcnt(5)
	v_lshlrev_b32_e32 v20, 16, v50
	v_and_b32_e32 v21, 0xffff0000, v50
	v_lshlrev_b32_e32 v16, 16, v48
	v_and_b32_e32 v17, 0xffff0000, v48
	v_lshlrev_b32_e32 v18, 16, v49
	v_and_b32_e32 v19, 0xffff0000, v49
	v_lshlrev_b32_e32 v22, 16, v51
	v_and_b32_e32 v23, 0xffff0000, v51
	s_waitcnt vmcnt(4)
	v_lshlrev_b32_e32 v24, 16, v52
	v_and_b32_e32 v25, 0xffff0000, v52
	v_lshlrev_b32_e32 v26, 16, v53
	v_and_b32_e32 v27, 0xffff0000, v53
	v_lshlrev_b32_e32 v28, 16, v54
	v_and_b32_e32 v29, 0xffff0000, v54
	v_lshlrev_b32_e32 v30, 16, v55
	v_and_b32_e32 v31, 0xffff0000, v55
	v_pk_fma_f32 v[14:15], v[14:15], v[18:19], v[26:27]
	v_pk_fma_f32 v[12:13], v[12:13], v[16:17], v[24:25]
	v_pk_fma_f32 v[16:17], v[10:11], v[22:23], v[30:31]
	v_pk_fma_f32 v[10:11], v[8:9], v[20:21], v[28:29]
	v_cvt_pk_bf16_f32 v8, v12, v13
	v_cvt_pk_bf16_f32 v9, v14, v15
	v_cvt_pk_bf16_f32 v10, v10, v11
	v_cvt_pk_bf16_f32 v11, v16, v17
	global_store_dwordx4 v[66:67], v[8:11], off
	s_waitcnt vmcnt(4)
	v_lshlrev_b32_e32 v12, 16, v58
	v_and_b32_e32 v13, 0xffff0000, v58
	v_lshlrev_b32_e32 v8, 16, v56
	v_and_b32_e32 v9, 0xffff0000, v56
	v_lshlrev_b32_e32 v10, 16, v57
	v_and_b32_e32 v11, 0xffff0000, v57
	v_lshlrev_b32_e32 v14, 16, v59
	v_and_b32_e32 v15, 0xffff0000, v59
	s_waitcnt vmcnt(3)
	v_lshlrev_b32_e32 v16, 16, v60
	v_and_b32_e32 v17, 0xffff0000, v60
	v_lshlrev_b32_e32 v18, 16, v61
	v_and_b32_e32 v19, 0xffff0000, v61
	v_lshlrev_b32_e32 v20, 16, v62
	v_and_b32_e32 v21, 0xffff0000, v62
	v_lshlrev_b32_e32 v22, 16, v63
	v_and_b32_e32 v23, 0xffff0000, v63
	v_pk_fma_f32 v[6:7], v[6:7], v[10:11], v[18:19]
	v_pk_fma_f32 v[4:5], v[4:5], v[8:9], v[16:17]
	v_pk_fma_f32 v[8:9], v[2:3], v[14:15], v[22:23]
	v_pk_fma_f32 v[2:3], v[0:1], v[12:13], v[20:21]
	v_cvt_pk_bf16_f32 v0, v4, v5
	v_cvt_pk_bf16_f32 v1, v6, v7
	v_cvt_pk_bf16_f32 v2, v2, v3
	v_cvt_pk_bf16_f32 v3, v8, v9
	global_store_dwordx4 v[66:67], v[0:3], off offset:256
